# MoBA tile loop+epilogue hand-written in transposed form (S^T=KQ^T, O^T=V^T P^T, P in registers, permlane-swap reductions, scalar tile walk); SWIGLU k-loops hand-scheduled (both instances)
# speedup vs baseline: 1.2280x; 1.0500x over previous
.LBB0_139:
	s_barrier
	s_lshl_b32 s14, s0, 7
	s_lshl_b32 s0, s13, 7
	v_lshrrev_b32_e32 v64, 4, v182
	v_xor_b32_e32 v64, v64, v182
	v_and_b32_e32 v64, 7, v64
	v_lshlrev_b32_e32 v64, 4, v64
	v_lshrrev_b32_e32 v65, 3, v182
	v_lshrrev_b32_e32 v68, 6, v182
	v_lshl_or_b32 v91, v65, 11, v64
	v_readfirstlane_b32 s5, v68
	v_add_u32_e32 v112, 0x10000, v91
	v_add_u32_e32 v148, 0x20000, v91
	v_add_u32_e32 v149, 0x30000, v91
	v_add3_u32 v64, v84, v85, v83
	v_add3_u32 v65, v81, v85, v83
	v_add3_u32 v66, v84, v82, v83
	v_add3_u32 v67, v81, v82, v83
	s_lshl_b32 s5, s5, 10
	s_lshl_b32 s4, s14, 11
	s_add_u32 s8, s40, s4
	s_addc_u32 s9, s41, 0
	s_lshl_b32 s4, s0, 11
	s_add_u32 s10, s66, s4
	s_addc_u32 s11, s67, 0
	s_mov_b32 m0, s5
	s_add_u32 s4, s5, 0x1000
	global_load_lds_dwordx4 v91, s[8:9]
	s_mov_b32 m0, s4
	s_add_u32 s4, s5, 0x2000
	global_load_lds_dwordx4 v112, s[8:9]
	s_mov_b32 m0, s4
	s_add_u32 s4, s5, 0x3000
	global_load_lds_dwordx4 v148, s[8:9]
	s_mov_b32 m0, s4
	s_add_u32 s4, s5, 0x4000
	global_load_lds_dwordx4 v149, s[8:9]
	s_mov_b32 m0, s4
	s_add_u32 s4, s5, 0x5000
	global_load_lds_dwordx4 v91, s[10:11]
	s_mov_b32 m0, s4
	s_add_u32 s4, s5, 0x6000
	global_load_lds_dwordx4 v112, s[10:11]
	s_mov_b32 m0, s4
	s_add_u32 s4, s5, 0x7000
	global_load_lds_dwordx4 v148, s[10:11]
	s_mov_b32 m0, s4
	s_add_u32 s15, s5, 0x8000
	global_load_lds_dwordx4 v149, s[10:11]
	s_movk_i32 s16, 15
	v_mov_b32_e32 v0, 0
	v_mov_b32_e32 v1, v0
	v_mov_b32_e32 v2, v0
	v_mov_b32_e32 v3, v0
	v_mov_b32_e32 v4, v0
	v_mov_b32_e32 v5, v0
	v_mov_b32_e32 v6, v0
	v_mov_b32_e32 v7, v0
	v_mov_b32_e32 v8, v0
	v_mov_b32_e32 v9, v0
	v_mov_b32_e32 v10, v0
	v_mov_b32_e32 v11, v0
	v_mov_b32_e32 v12, v0
	v_mov_b32_e32 v13, v0
	v_mov_b32_e32 v14, v0
	v_mov_b32_e32 v15, v0
	v_mov_b32_e32 v16, v0
	v_mov_b32_e32 v17, v0
	v_mov_b32_e32 v18, v0
	v_mov_b32_e32 v19, v0
	v_mov_b32_e32 v20, v0
	v_mov_b32_e32 v21, v0
	v_mov_b32_e32 v22, v0
	v_mov_b32_e32 v23, v0
	v_mov_b32_e32 v24, v0
	v_mov_b32_e32 v25, v0
	v_mov_b32_e32 v26, v0
	v_mov_b32_e32 v27, v0
	v_mov_b32_e32 v28, v0
	v_mov_b32_e32 v29, v0
	v_mov_b32_e32 v30, v0
	v_mov_b32_e32 v31, v0
	v_mov_b32_e32 v32, v0
	v_mov_b32_e32 v33, v0
	v_mov_b32_e32 v34, v0
	v_mov_b32_e32 v35, v0
	v_mov_b32_e32 v36, v0
	v_mov_b32_e32 v37, v0
	v_mov_b32_e32 v38, v0
	v_mov_b32_e32 v39, v0
	v_mov_b32_e32 v40, v0
	v_mov_b32_e32 v41, v0
	v_mov_b32_e32 v42, v0
	v_mov_b32_e32 v43, v0
	v_mov_b32_e32 v44, v0
	v_mov_b32_e32 v45, v0
	v_mov_b32_e32 v46, v0
	v_mov_b32_e32 v47, v0
	v_mov_b32_e32 v48, v0
	v_mov_b32_e32 v49, v0
	v_mov_b32_e32 v50, v0
	v_mov_b32_e32 v51, v0
	v_mov_b32_e32 v52, v0
	v_mov_b32_e32 v53, v0
	v_mov_b32_e32 v54, v0
	v_mov_b32_e32 v55, v0
	v_mov_b32_e32 v56, v0
	v_mov_b32_e32 v57, v0
	v_mov_b32_e32 v58, v0
	v_mov_b32_e32 v59, v0
	v_mov_b32_e32 v60, v0
	v_mov_b32_e32 v61, v0
	v_mov_b32_e32 v62, v0
	v_mov_b32_e32 v63, v0
.Lgk_sw1:
	s_waitcnt vmcnt(0)
	s_barrier
	ds_read_b128 v[96:99], v66 offset:16384
	ds_read_b128 v[68:71], v64
	ds_read_b128 v[100:103], v66 offset:18432
	ds_read_b128 v[104:107], v66 offset:20480
	ds_read_b128 v[108:111], v66 offset:22528
	ds_read_b128 v[72:75], v64 offset:2048
	ds_read_b128 v[76:79], v64 offset:4096
	ds_read_b128 v[92:95], v64 offset:6144
	s_add_u32 s8, s8, 0x80
	s_addc_u32 s9, s9, 0
	s_add_u32 s10, s10, 0x80
	s_addc_u32 s11, s11, 0
	s_mov_b32 m0, s15
	s_add_u32 s4, s15, 0x1000
	global_load_lds_dwordx4 v91, s[8:9]
	s_mov_b32 m0, s4
	s_add_u32 s4, s15, 0x2000
	global_load_lds_dwordx4 v112, s[8:9]
	s_mov_b32 m0, s4
	s_add_u32 s4, s15, 0x3000
	global_load_lds_dwordx4 v148, s[8:9]
	s_mov_b32 m0, s4
	s_add_u32 s4, s15, 0x4000
	global_load_lds_dwordx4 v149, s[8:9]
	s_mov_b32 m0, s4
	s_add_u32 s4, s15, 0x5000
	global_load_lds_dwordx4 v91, s[10:11]
	s_mov_b32 m0, s4
	s_add_u32 s4, s15, 0x6000
	global_load_lds_dwordx4 v112, s[10:11]
	s_mov_b32 m0, s4
	s_add_u32 s4, s15, 0x7000
	global_load_lds_dwordx4 v148, s[10:11]
	s_mov_b32 m0, s4
	s_sub_u32 s16, s16, 1
	global_load_lds_dwordx4 v149, s[10:11]
	s_xor_b32 s15, s15, 0x8000
	s_waitcnt lgkmcnt(3)
	v_mfma_f32_16x16x32_f16 v[60:63], v[68:71], v[96:99], v[60:63]
	v_mfma_f32_16x16x32_f16 v[56:59], v[68:71], v[100:103], v[56:59]
	v_mfma_f32_16x16x32_f16 v[52:55], v[68:71], v[104:107], v[52:55]
	v_mfma_f32_16x16x32_f16 v[48:51], v[68:71], v[108:111], v[48:51]
	ds_read_b128 v[132:135], v67 offset:16384
	ds_read_b128 v[116:119], v65
	s_waitcnt lgkmcnt(4)
	v_mfma_f32_16x16x32_f16 v[44:47], v[72:75], v[96:99], v[44:47]
	v_mfma_f32_16x16x32_f16 v[40:43], v[72:75], v[100:103], v[40:43]
	v_mfma_f32_16x16x32_f16 v[36:39], v[72:75], v[104:107], v[36:39]
	v_mfma_f32_16x16x32_f16 v[32:35], v[72:75], v[108:111], v[32:35]
	ds_read_b128 v[136:139], v67 offset:18432
	ds_read_b128 v[140:143], v67 offset:20480
	s_waitcnt lgkmcnt(5)
	v_mfma_f32_16x16x32_f16 v[28:31], v[76:79], v[96:99], v[28:31]
	v_mfma_f32_16x16x32_f16 v[24:27], v[76:79], v[100:103], v[24:27]
	v_mfma_f32_16x16x32_f16 v[20:23], v[76:79], v[104:107], v[20:23]
	v_mfma_f32_16x16x32_f16 v[16:19], v[76:79], v[108:111], v[16:19]
	ds_read_b128 v[144:147], v67 offset:22528
	ds_read_b128 v[120:123], v65 offset:2048
	s_waitcnt lgkmcnt(6)
	v_mfma_f32_16x16x32_f16 v[12:15], v[92:95], v[96:99], v[12:15]
	v_mfma_f32_16x16x32_f16 v[8:11], v[92:95], v[100:103], v[8:11]
	v_mfma_f32_16x16x32_f16 v[4:7], v[92:95], v[104:107], v[4:7]
	v_mfma_f32_16x16x32_f16 v[0:3], v[92:95], v[108:111], v[0:3]
	ds_read_b128 v[124:127], v65 offset:4096
	ds_read_b128 v[128:131], v65 offset:6144
	v_xor_b32_e32 v64, 0x8000, v64
	v_xor_b32_e32 v66, 0x8000, v66
	s_waitcnt lgkmcnt(3)
	v_mfma_f32_16x16x32_f16 v[60:63], v[116:119], v[132:135], v[60:63]
	v_mfma_f32_16x16x32_f16 v[56:59], v[116:119], v[136:139], v[56:59]
	v_mfma_f32_16x16x32_f16 v[52:55], v[116:119], v[140:143], v[52:55]
	v_mfma_f32_16x16x32_f16 v[48:51], v[116:119], v[144:147], v[48:51]
	v_xor_b32_e32 v65, 0x8000, v65
	v_xor_b32_e32 v67, 0x8000, v67
	s_waitcnt lgkmcnt(2)
	v_mfma_f32_16x16x32_f16 v[44:47], v[120:123], v[132:135], v[44:47]
	v_mfma_f32_16x16x32_f16 v[40:43], v[120:123], v[136:139], v[40:43]
	v_mfma_f32_16x16x32_f16 v[36:39], v[120:123], v[140:143], v[36:39]
	v_mfma_f32_16x16x32_f16 v[32:35], v[120:123], v[144:147], v[32:35]
	s_waitcnt lgkmcnt(1)
	v_mfma_f32_16x16x32_f16 v[28:31], v[124:127], v[132:135], v[28:31]
	v_mfma_f32_16x16x32_f16 v[24:27], v[124:127], v[136:139], v[24:27]
	v_mfma_f32_16x16x32_f16 v[20:23], v[124:127], v[140:143], v[20:23]
	v_mfma_f32_16x16x32_f16 v[16:19], v[124:127], v[144:147], v[16:19]
	s_cmp_lg_u32 s16, 0
	s_waitcnt lgkmcnt(0)
	v_mfma_f32_16x16x32_f16 v[12:15], v[128:131], v[132:135], v[12:15]
	v_mfma_f32_16x16x32_f16 v[8:11], v[128:131], v[136:139], v[8:11]
	v_mfma_f32_16x16x32_f16 v[4:7], v[128:131], v[140:143], v[4:7]
	v_mfma_f32_16x16x32_f16 v[0:3], v[128:131], v[144:147], v[0:3]
	s_cbranch_scc1 .Lgk_sw1
	s_waitcnt vmcnt(0)
	s_barrier
	ds_read_b128 v[64:67], v90 offset:32768
	ds_read_b128 v[68:71], v89 offset:49152
	ds_read_b128 v[72:75], v89 offset:51200
	ds_read_b128 v[76:79], v89 offset:53248
	ds_read_b128 v[92:95], v89 offset:55296
	ds_read_b128 v[96:99], v90 offset:34816
	ds_read_b128 v[100:103], v88 offset:32768
	ds_read_b128 v[104:107], v88 offset:34816
	ds_read_b128 v[108:111], v87 offset:51200
	ds_read_b128 v[116:119], v87 offset:49152
	s_waitcnt lgkmcnt(8)
	v_mfma_f32_16x16x32_f16 v[60:63], v[64:67], v[68:71], v[60:63]
	ds_read_b128 v[124:127], v87 offset:55296
	ds_read_b128 v[128:131], v87 offset:53248
	ds_read_b128 v[132:135], v88 offset:38912
	ds_read_b128 v[136:139], v88 offset:36864
	s_add_i32 s12, s12, s60
	s_cmp_ge_i32 s12, s62
	s_waitcnt lgkmcnt(4)
	v_mfma_f32_16x16x32_f16 v[60:63], v[100:103], v[116:119], v[60:63]
	v_mfma_f32_16x16x32_f16 v[56:59], v[64:67], v[72:75], v[56:59]
	v_mfma_f32_16x16x32_f16 v[52:55], v[64:67], v[76:79], v[52:55]
	v_mfma_f32_16x16x32_f16 v[64:67], v[64:67], v[92:95], v[48:51]
	v_mfma_f32_16x16x32_f16 v[120:123], v[96:99], v[72:75], v[40:43]
	s_nop 2
	ds_read_b128 v[40:43], v90 offset:38912
	ds_read_b128 v[140:143], v90 offset:36864
	v_mul_f32_e32 v48, 0xbfb8aa3b, v60
	v_exp_f32_e32 v49, v48
	s_waitcnt lgkmcnt(0)
	v_mfma_f32_16x16x32_f16 v[28:31], v[140:143], v[68:71], v[28:31]
	v_add_f32_e32 v51, 1.0, v49
	v_lshl_or_b32 v48, s13, 6, v86
	v_add_u32_e32 v50, s14, v80
	v_mfma_f32_16x16x32_f16 v[144:147], v[140:143], v[72:75], v[24:27]
	v_ashrrev_i32_e32 v49, 31, v48
	v_lshl_add_u64 v[48:49], v[48:49], 1, s[30:31]
	v_mad_i64_i32 v[148:149], s[8:9], v50, s64, v[48:49]
	v_mfma_f32_16x16x32_f16 v[20:23], v[140:143], v[76:79], v[20:23]
	v_div_scale_f32 v24, vcc, v60, v51, v60
	v_mfma_f32_16x16x32_f16 v[140:143], v[140:143], v[92:95], v[16:19]
	s_nop 2
	v_mul_f32_e32 v17, 0xbfb8aa3b, v61
	v_mfma_f32_16x16x32_f16 v[44:47], v[96:99], v[68:71], v[44:47]
	v_exp_f32_e32 v17, v17
	v_mfma_f32_16x16x32_f16 v[36:39], v[96:99], v[76:79], v[36:39]
	v_mfma_f32_16x16x32_f16 v[96:99], v[96:99], v[92:95], v[32:35]
	s_nop 2
	v_div_scale_f32 v32, s[8:9], v51, v51, v60
	v_rcp_f32_e32 v33, v32
	v_mfma_f32_16x16x32_f16 v[12:15], v[40:43], v[68:71], v[12:15]
	v_fma_f32 v34, -v32, v33, 1.0
	v_mfma_f32_16x16x32_f16 v[68:71], v[40:43], v[72:75], v[8:11]
	v_fmac_f32_e32 v33, v34, v33
	v_mul_f32_e32 v25, v24, v33
	v_fma_f32 v26, -v32, v25, v24
	v_add_f32_e32 v8, 1.0, v17
	v_div_scale_f32 v9, s[8:9], v8, v8, v61
	v_rcp_f32_e32 v10, v9
	v_fmac_f32_e32 v25, v26, v33
	v_fma_f32 v16, -v32, v25, v24
	v_mfma_f32_16x16x32_f16 v[72:75], v[40:43], v[92:95], v[0:3]
	v_div_fmas_f32 v16, v16, v33, v25
	v_div_fixup_f32 v16, v16, v51, v60
	v_or_b32_e32 v51, 2, v50
	v_fma_f32 v1, -v9, v10, 1.0
	v_fmac_f32_e32 v10, v1, v10
	v_div_scale_f32 v1, vcc, v61, v8, v61
	v_mul_f32_e32 v2, v1, v10
	v_fma_f32 v3, -v9, v2, v1
	v_fmac_f32_e32 v2, v3, v10
	v_fma_f32 v1, -v9, v2, v1
	v_div_fmas_f32 v1, v1, v10, v2
	v_mul_f32_e32 v2, 0xbfb8aa3b, v62
	v_mfma_f32_16x16x32_f16 v[52:55], v[100:103], v[128:131], v[52:55]
	v_exp_f32_e32 v2, v2
	v_or_b32_e32 v0, 1, v50
	v_div_fixup_f32 v1, v1, v8, v61
	v_mfma_f32_16x16x32_f16 v[4:7], v[40:43], v[76:79], v[4:7]
	v_mfma_f32_16x16x32_f16 v[56:59], v[100:103], v[108:111], v[56:59]
	s_nop 2
	v_mul_f32_e32 v16, v52, v16
	v_mul_f32_e32 v1, v53, v1
	v_mad_i64_i32 v[52:53], s[8:9], v0, s64, v[48:49]
	v_add_f32_e32 v0, 1.0, v2
	v_med3_f32 v1, v1, s57, v194
	v_div_scale_f32 v2, s[8:9], v0, v0, v62
	v_cvt_f16_f32_e32 v1, v1
	v_rcp_f32_e32 v3, v2
	v_mfma_f32_16x16x32_f16 v[64:67], v[100:103], v[124:127], v[64:67]
	v_med3_f32 v16, v16, s57, v194
	global_store_short v[52:53], v1, off
	v_fma_f32 v1, -v2, v3, 1.0
	v_fmac_f32_e32 v3, v1, v3
	v_div_scale_f32 v1, vcc, v62, v0, v62
	v_mul_f32_e32 v60, v1, v3
	v_fma_f32 v8, -v2, v60, v1
	v_fmac_f32_e32 v60, v8, v3
	v_fma_f32 v1, -v2, v60, v1
	v_div_fmas_f32 v1, v1, v3, v60
	v_mfma_f32_16x16x32_f16 v[8:11], v[132:135], v[116:119], v[12:15]
	v_cvt_f16_f32_e32 v16, v16
	global_store_short v[148:149], v16, off
	s_nop 0
	v_div_fixup_f32 v12, v1, v0, v62
	v_mul_f32_e32 v54, v54, v12
	v_mul_f32_e32 v12, 0xbfb8aa3b, v63
	v_exp_f32_e32 v60, v12
	v_mfma_f32_16x16x32_f16 v[0:3], v[132:135], v[108:111], v[68:71]
	v_add_f32_e32 v62, 1.0, v60
	v_mfma_f32_16x16x32_f16 v[12:15], v[132:135], v[128:131], v[4:7]
	s_nop 0
	v_div_scale_f32 v68, s[8:9], v62, v62, v63
	v_rcp_f32_e32 v69, v68
	v_med3_f32 v4, v54, s57, v194
	v_cvt_f16_f32_e32 v54, v4
	v_mad_i64_i32 v[60:61], s[8:9], v51, s64, v[48:49]
	v_or_b32_e32 v51, 3, v50
	global_store_short v[60:61], v54, off
	v_fma_f32 v54, -v68, v69, 1.0
	v_fmac_f32_e32 v69, v54, v69
	v_div_scale_f32 v54, vcc, v63, v62, v63
	v_mul_f32_e32 v70, v54, v69
	v_fma_f32 v71, -v68, v70, v54
	v_fmac_f32_e32 v70, v71, v69
	v_fma_f32 v54, -v68, v70, v54
	v_mul_f32_e32 v68, 0xbfb8aa3b, v56
	v_exp_f32_e32 v68, v68
	v_div_fmas_f32 v54, v54, v69, v70
	v_div_fixup_f32 v54, v54, v62, v63
	v_mul_f32_e32 v54, v55, v54
	v_add_f32_e32 v62, 1.0, v68
	v_div_scale_f32 v63, s[8:9], v62, v62, v56
	v_rcp_f32_e32 v68, v63
	v_med3_f32 v54, v54, s57, v194
	v_cvt_f16_f32_e32 v69, v54
	v_mad_i64_i32 v[54:55], s[8:9], v51, s64, v[48:49]
	v_fma_f32 v51, -v63, v68, 1.0
	v_fmac_f32_e32 v68, v51, v68
	v_div_scale_f32 v51, vcc, v56, v62, v56
	v_mul_f32_e32 v70, v51, v68
	v_fma_f32 v71, -v63, v70, v51
	v_fmac_f32_e32 v70, v71, v68
	v_fma_f32 v51, -v63, v70, v51
	v_mul_f32_e32 v63, 0xbfb8aa3b, v57
	v_exp_f32_e32 v63, v63
	v_div_fmas_f32 v51, v51, v68, v70
	v_div_fixup_f32 v51, v51, v62, v56
	v_mul_f32_e32 v51, v64, v51
	v_add_f32_e32 v56, 1.0, v63
	v_div_scale_f32 v62, s[8:9], v56, v56, v57
	v_rcp_f32_e32 v63, v62
	v_med3_f32 v51, v51, s57, v194
	v_cvt_f16_f32_e32 v51, v51
	v_mfma_f32_16x16x32_f16 v[40:43], v[104:107], v[116:119], v[44:47]
	v_fma_f32 v64, -v62, v63, 1.0
	v_fmac_f32_e32 v63, v64, v63
	v_div_scale_f32 v64, vcc, v57, v56, v57
	v_mul_f32_e32 v68, v64, v63
	v_fma_f32 v70, -v62, v68, v64
	v_fmac_f32_e32 v68, v70, v63
	v_fma_f32 v62, -v62, v68, v64
	v_div_fmas_f32 v62, v62, v63, v68
	v_div_fixup_f32 v56, v62, v56, v57
	v_mul_f32_e32 v57, 0xbfb8aa3b, v58
	v_exp_f32_e32 v57, v57
	v_mul_f32_e32 v56, v65, v56
	v_med3_f32 v56, v56, s57, v194
	v_cvt_f16_f32_e32 v56, v56
	v_add_f32_e32 v57, 1.0, v57
	v_div_scale_f32 v62, s[8:9], v57, v57, v58
	v_rcp_f32_e32 v63, v62
	global_store_short v[54:55], v69, off
	global_store_short v[148:149], v51, off offset:32
	global_store_short v[52:53], v56, off offset:32
	v_mfma_f32_16x16x32_f16 v[44:47], v[104:107], v[128:131], v[36:39]
	v_fma_f32 v51, -v62, v63, 1.0
	v_fmac_f32_e32 v63, v51, v63
	v_div_scale_f32 v51, vcc, v58, v57, v58
	v_mul_f32_e32 v52, v51, v63
	v_fma_f32 v53, -v62, v52, v51
	v_fmac_f32_e32 v52, v53, v63
	v_mul_f32_e32 v53, 0xbfb8aa3b, v59
	v_exp_f32_e32 v53, v53
	v_fma_f32 v51, -v62, v52, v51
	v_div_fmas_f32 v51, v51, v63, v52
	v_div_fixup_f32 v51, v51, v57, v58
	v_add_f32_e32 v52, 1.0, v53
	v_div_scale_f32 v53, s[8:9], v52, v52, v59
	v_rcp_f32_e32 v56, v53
	v_mul_f32_e32 v51, v66, v51
	v_med3_f32 v51, v51, s57, v194
	v_cvt_f16_f32_e32 v51, v51
	v_fma_f32 v57, -v53, v56, 1.0
	v_fmac_f32_e32 v56, v57, v56
	v_div_scale_f32 v57, vcc, v59, v52, v59
	v_mul_f32_e32 v58, v57, v56
	v_fma_f32 v62, -v53, v58, v57
	v_fmac_f32_e32 v58, v62, v56
	v_fma_f32 v53, -v53, v58, v57
	v_div_fmas_f32 v53, v53, v56, v58
	v_div_fixup_f32 v52, v53, v52, v59
	v_mul_f32_e32 v53, 0xbfb8aa3b, v40
	v_exp_f32_e32 v53, v53
	v_mul_f32_e32 v52, v67, v52
	v_med3_f32 v52, v52, s57, v194
	v_cvt_f16_f32_e32 v52, v52
	v_add_f32_e32 v53, 1.0, v53
	v_div_scale_f32 v56, s[8:9], v53, v53, v40
	v_rcp_f32_e32 v57, v56
	global_store_short v[60:61], v51, off offset:32
	global_store_short v[54:55], v52, off offset:32
	v_or_b32_e32 v51, 16, v50
	v_mfma_f32_16x16x32_f16 v[32:35], v[104:107], v[108:111], v[120:123]
	v_fma_f32 v52, -v56, v57, 1.0
	v_fmac_f32_e32 v57, v52, v57
	v_div_scale_f32 v52, vcc, v40, v53, v40
	v_mul_f32_e32 v54, v52, v57
	v_fma_f32 v55, -v56, v54, v52
	v_fmac_f32_e32 v54, v55, v57
	v_fma_f32 v52, -v56, v54, v52
	v_div_fmas_f32 v52, v52, v57, v54
	v_div_fixup_f32 v40, v52, v53, v40
	v_mul_f32_e32 v52, 0xbfb8aa3b, v41
	v_exp_f32_e32 v52, v52
	v_mul_f32_e32 v40, v44, v40
	v_mfma_f32_16x16x32_f16 v[36:39], v[104:107], v[124:127], v[96:99]
	v_med3_f32 v40, v40, s57, v194
	v_add_f32_e32 v44, 1.0, v52
	v_div_scale_f32 v54, s[8:9], v44, v44, v41
	v_rcp_f32_e32 v55, v54
	v_mad_i64_i32 v[52:53], s[8:9], v51, s64, v[48:49]
	v_cvt_f16_f32_e32 v40, v40
	v_fma_f32 v51, -v54, v55, 1.0
	v_fmac_f32_e32 v55, v51, v55
	v_div_scale_f32 v51, vcc, v41, v44, v41
	v_mul_f32_e32 v56, v51, v55
	v_fma_f32 v57, -v54, v56, v51
	v_fmac_f32_e32 v56, v57, v55
	v_fma_f32 v51, -v54, v56, v51
	v_div_fmas_f32 v51, v51, v55, v56
	v_div_fixup_f32 v41, v51, v44, v41
	v_mul_f32_e32 v44, 0xbfb8aa3b, v42
	v_exp_f32_e32 v44, v44
	v_mul_f32_e32 v41, v45, v41
	v_med3_f32 v41, v41, s57, v194
	v_cvt_f16_f32_e32 v45, v41
	v_add_f32_e32 v44, 1.0, v44
	v_div_scale_f32 v51, s[8:9], v44, v44, v42
	v_rcp_f32_e32 v54, v51
	global_store_short v[52:53], v40, off
	v_or_b32_e32 v40, 17, v50
	v_mad_i64_i32 v[40:41], s[8:9], v40, s64, v[48:49]
	v_fma_f32 v55, -v51, v54, 1.0
	v_fmac_f32_e32 v54, v55, v54
	v_div_scale_f32 v55, vcc, v42, v44, v42
	v_mul_f32_e32 v56, v55, v54
	v_fma_f32 v57, -v51, v56, v55
	v_fmac_f32_e32 v56, v57, v54
	v_fma_f32 v51, -v51, v56, v55
	v_div_fmas_f32 v51, v51, v54, v56
	v_div_fixup_f32 v42, v51, v44, v42
	v_mul_f32_e32 v44, 0xbfb8aa3b, v43
	v_exp_f32_e32 v44, v44
	v_mul_f32_e32 v42, v46, v42
	v_med3_f32 v42, v42, s57, v194
	v_cvt_f16_f32_e32 v42, v42
	v_add_f32_e32 v46, 1.0, v44
	v_div_scale_f32 v51, s[8:9], v46, v46, v43
	v_rcp_f32_e32 v54, v51
	global_store_short v[40:41], v45, off
	v_or_b32_e32 v45, 18, v50
	v_mad_i64_i32 v[44:45], s[8:9], v45, s64, v[48:49]
	v_fma_f32 v55, -v51, v54, 1.0
	v_fmac_f32_e32 v54, v55, v54
	v_div_scale_f32 v55, vcc, v43, v46, v43
	v_mul_f32_e32 v56, v55, v54
	v_fma_f32 v57, -v51, v56, v55
	v_fmac_f32_e32 v56, v57, v54
	v_fma_f32 v51, -v51, v56, v55
	v_div_fmas_f32 v51, v51, v54, v56
	v_mul_f32_e32 v54, 0xbfb8aa3b, v32
	v_exp_f32_e32 v54, v54
	v_div_fixup_f32 v43, v51, v46, v43
	v_mul_f32_e32 v43, v47, v43
	v_med3_f32 v43, v43, s57, v194
	v_add_f32_e32 v46, 1.0, v54
	v_div_scale_f32 v47, s[8:9], v46, v46, v32
	v_rcp_f32_e32 v51, v47
	v_cvt_f16_f32_e32 v54, v43
	global_store_short v[44:45], v42, off
	v_or_b32_e32 v42, 19, v50
	v_fma_f32 v55, -v47, v51, 1.0
	v_fmac_f32_e32 v51, v55, v51
	v_div_scale_f32 v55, vcc, v32, v46, v32
	v_mul_f32_e32 v56, v55, v51
	v_fma_f32 v57, -v47, v56, v55
	v_fmac_f32_e32 v56, v57, v51
	v_fma_f32 v47, -v47, v56, v55
	v_mul_f32_e32 v55, 0xbfb8aa3b, v33
	v_exp_f32_e32 v55, v55
	v_div_fmas_f32 v47, v47, v51, v56
	v_div_fixup_f32 v32, v47, v46, v32
	v_mul_f32_e32 v32, v36, v32
	v_add_f32_e32 v46, 1.0, v55
	v_div_scale_f32 v47, s[8:9], v46, v46, v33
	v_rcp_f32_e32 v51, v47
	v_med3_f32 v32, v32, s57, v194
	v_cvt_f16_f32_e32 v32, v32
	v_mad_i64_i32 v[42:43], s[8:9], v42, s64, v[48:49]
	v_fma_f32 v36, -v47, v51, 1.0
	v_fmac_f32_e32 v51, v36, v51
	v_div_scale_f32 v36, vcc, v33, v46, v33
	v_mul_f32_e32 v55, v36, v51
	v_fma_f32 v56, -v47, v55, v36
	v_fmac_f32_e32 v55, v56, v51
	v_fma_f32 v36, -v47, v55, v36
	v_div_fmas_f32 v36, v36, v51, v55
	v_div_fixup_f32 v33, v36, v46, v33
	v_mul_f32_e32 v36, 0xbfb8aa3b, v34
	v_exp_f32_e32 v36, v36
	v_mul_f32_e32 v33, v37, v33
	v_med3_f32 v33, v33, s57, v194
	v_cvt_f16_f32_e32 v33, v33
	v_add_f32_e32 v36, 1.0, v36
	v_div_scale_f32 v37, s[8:9], v36, v36, v34
	v_rcp_f32_e32 v46, v37
	global_store_short v[42:43], v54, off
	global_store_short v[52:53], v32, off offset:32
	global_store_short v[40:41], v33, off offset:32
	v_mfma_f32_16x16x32_f16 v[24:27], v[136:139], v[116:119], v[28:31]
	v_fma_f32 v32, -v37, v46, 1.0
	v_fmac_f32_e32 v46, v32, v46
	v_div_scale_f32 v32, vcc, v34, v36, v34
	v_mul_f32_e32 v33, v32, v46
	v_fma_f32 v40, -v37, v33, v32
	v_fmac_f32_e32 v33, v40, v46
	v_fma_f32 v32, -v37, v33, v32
	v_mul_f32_e32 v37, 0xbfb8aa3b, v35
	v_exp_f32_e32 v37, v37
	v_div_fmas_f32 v32, v32, v46, v33
	v_div_fixup_f32 v32, v32, v36, v34
	v_mul_f32_e32 v32, v38, v32
	v_add_f32_e32 v33, 1.0, v37
	v_div_scale_f32 v34, s[8:9], v33, v33, v35
	v_rcp_f32_e32 v36, v34
	v_med3_f32 v32, v32, s57, v194
	v_cvt_f16_f32_e32 v32, v32
	v_mfma_f32_16x16x32_f16 v[28:31], v[136:139], v[128:131], v[20:23]
	v_fma_f32 v37, -v34, v36, 1.0
	v_fmac_f32_e32 v36, v37, v36
	v_div_scale_f32 v37, vcc, v35, v33, v35
	v_mul_f32_e32 v38, v37, v36
	v_fma_f32 v40, -v34, v38, v37
	v_fmac_f32_e32 v38, v40, v36
	v_fma_f32 v34, -v34, v38, v37
	v_div_fmas_f32 v34, v34, v36, v38
	v_div_fixup_f32 v33, v34, v33, v35
	v_mul_f32_e32 v34, 0xbfb8aa3b, v24
	v_exp_f32_e32 v34, v34
	v_mul_f32_e32 v33, v39, v33
	v_med3_f32 v33, v33, s57, v194
	v_cvt_f16_f32_e32 v33, v33
	v_add_f32_e32 v34, 1.0, v34
	v_div_scale_f32 v35, s[8:9], v34, v34, v24
	v_rcp_f32_e32 v36, v35
	global_store_short v[44:45], v32, off offset:32
	global_store_short v[42:43], v33, off offset:32
	v_mfma_f32_16x16x32_f16 v[16:19], v[136:139], v[108:111], v[144:147]
	v_or_b32_e32 v32, 32, v50
	v_fma_f32 v33, -v35, v36, 1.0
	v_fmac_f32_e32 v36, v33, v36
	v_div_scale_f32 v33, vcc, v24, v34, v24
	v_mul_f32_e32 v37, v33, v36
	v_fma_f32 v38, -v35, v37, v33
	v_fmac_f32_e32 v37, v38, v36
	v_fma_f32 v33, -v35, v37, v33
	v_div_fmas_f32 v33, v33, v36, v37
	v_div_fixup_f32 v24, v33, v34, v24
	v_mul_f32_e32 v33, 0xbfb8aa3b, v25
	v_exp_f32_e32 v33, v33
	v_mul_f32_e32 v24, v28, v24
	v_mfma_f32_16x16x32_f16 v[20:23], v[136:139], v[124:127], v[140:143]
	v_med3_f32 v24, v24, s57, v194
	v_add_f32_e32 v28, 1.0, v33
	v_div_scale_f32 v34, s[8:9], v28, v28, v25
	v_rcp_f32_e32 v35, v34
	v_cvt_f16_f32_e32 v24, v24
	v_mad_i64_i32 v[32:33], s[8:9], v32, s64, v[48:49]
	v_fma_f32 v36, -v34, v35, 1.0
	v_fmac_f32_e32 v35, v36, v35
	v_div_scale_f32 v36, vcc, v25, v28, v25
	v_mul_f32_e32 v37, v36, v35
	v_fma_f32 v38, -v34, v37, v36
	v_fmac_f32_e32 v37, v38, v35
	v_fma_f32 v34, -v34, v37, v36
	v_div_fmas_f32 v34, v34, v35, v37
	v_div_fixup_f32 v25, v34, v28, v25
	v_mul_f32_e32 v28, 0xbfb8aa3b, v26
	v_exp_f32_e32 v28, v28
	v_mul_f32_e32 v25, v29, v25
	v_med3_f32 v25, v25, s57, v194
	v_cvt_f16_f32_e32 v29, v25
	v_add_f32_e32 v28, 1.0, v28
	v_div_scale_f32 v34, s[8:9], v28, v28, v26
	v_rcp_f32_e32 v35, v34
	global_store_short v[32:33], v24, off
	v_or_b32_e32 v24, 33, v50
	v_mad_i64_i32 v[24:25], s[8:9], v24, s64, v[48:49]
	v_fma_f32 v36, -v34, v35, 1.0
	v_fmac_f32_e32 v35, v36, v35
	v_div_scale_f32 v36, vcc, v26, v28, v26
	v_mul_f32_e32 v37, v36, v35
	v_fma_f32 v38, -v34, v37, v36
	v_fmac_f32_e32 v37, v38, v35
	v_fma_f32 v34, -v34, v37, v36
	v_div_fmas_f32 v34, v34, v35, v37
	v_div_fixup_f32 v26, v34, v28, v26
	v_mul_f32_e32 v28, 0xbfb8aa3b, v27
	v_exp_f32_e32 v28, v28
	v_mul_f32_e32 v26, v30, v26
	v_med3_f32 v26, v26, s57, v194
	v_cvt_f16_f32_e32 v26, v26
	v_add_f32_e32 v30, 1.0, v28
	v_div_scale_f32 v34, s[8:9], v30, v30, v27
	v_rcp_f32_e32 v35, v34
	global_store_short v[24:25], v29, off
	v_or_b32_e32 v29, 34, v50
	v_mad_i64_i32 v[28:29], s[8:9], v29, s64, v[48:49]
	v_fma_f32 v36, -v34, v35, 1.0
	v_fmac_f32_e32 v35, v36, v35
	v_div_scale_f32 v36, vcc, v27, v30, v27
	v_mul_f32_e32 v37, v36, v35
	v_fma_f32 v38, -v34, v37, v36
	v_fmac_f32_e32 v37, v38, v35
	v_fma_f32 v34, -v34, v37, v36
	v_div_fmas_f32 v34, v34, v35, v37
	v_mul_f32_e32 v35, 0xbfb8aa3b, v16
	v_exp_f32_e32 v35, v35
	v_div_fixup_f32 v27, v34, v30, v27
	v_mul_f32_e32 v27, v31, v27
	v_med3_f32 v27, v27, s57, v194
	v_add_f32_e32 v30, 1.0, v35
	v_div_scale_f32 v31, s[8:9], v30, v30, v16
	v_rcp_f32_e32 v34, v31
	v_cvt_f16_f32_e32 v35, v27
	global_store_short v[28:29], v26, off
	v_or_b32_e32 v26, 35, v50
	v_fma_f32 v36, -v31, v34, 1.0
	v_fmac_f32_e32 v34, v36, v34
	v_div_scale_f32 v36, vcc, v16, v30, v16
	v_mul_f32_e32 v37, v36, v34
	v_fma_f32 v38, -v31, v37, v36
	v_fmac_f32_e32 v37, v38, v34
	v_fma_f32 v31, -v31, v37, v36
	v_mul_f32_e32 v36, 0xbfb8aa3b, v17
	v_exp_f32_e32 v36, v36
	v_div_fmas_f32 v31, v31, v34, v37
	v_div_fixup_f32 v16, v31, v30, v16
	v_mul_f32_e32 v16, v20, v16
	v_add_f32_e32 v30, 1.0, v36
	v_div_scale_f32 v31, s[8:9], v30, v30, v17
	v_rcp_f32_e32 v34, v31
	v_med3_f32 v16, v16, s57, v194
	v_cvt_f16_f32_e32 v16, v16
	v_mad_i64_i32 v[26:27], s[8:9], v26, s64, v[48:49]
	v_fma_f32 v20, -v31, v34, 1.0
	v_fmac_f32_e32 v34, v20, v34
	v_div_scale_f32 v20, vcc, v17, v30, v17
	v_mul_f32_e32 v36, v20, v34
	v_fma_f32 v37, -v31, v36, v20
	v_fmac_f32_e32 v36, v37, v34
	v_fma_f32 v20, -v31, v36, v20
	v_div_fmas_f32 v20, v20, v34, v36
	v_div_fixup_f32 v17, v20, v30, v17
	v_mul_f32_e32 v20, 0xbfb8aa3b, v18
	v_exp_f32_e32 v20, v20
	v_mul_f32_e32 v17, v21, v17
	v_med3_f32 v17, v17, s57, v194
	v_cvt_f16_f32_e32 v17, v17
	v_add_f32_e32 v20, 1.0, v20
	v_div_scale_f32 v21, s[8:9], v20, v20, v18
	v_rcp_f32_e32 v30, v21
	global_store_short v[26:27], v35, off
	global_store_short v[32:33], v16, off offset:32
	global_store_short v[24:25], v17, off offset:32
	v_mfma_f32_16x16x32_f16 v[4:7], v[132:135], v[124:127], v[72:75]
	v_fma_f32 v16, -v21, v30, 1.0
	v_fmac_f32_e32 v30, v16, v30
	v_div_scale_f32 v16, vcc, v18, v20, v18
	v_mul_f32_e32 v17, v16, v30
	v_fma_f32 v24, -v21, v17, v16
	v_fmac_f32_e32 v17, v24, v30
	v_fma_f32 v16, -v21, v17, v16
	v_mul_f32_e32 v21, 0xbfb8aa3b, v19
	v_exp_f32_e32 v21, v21
	v_div_fmas_f32 v16, v16, v30, v17
	v_div_fixup_f32 v16, v16, v20, v18
	v_mul_f32_e32 v16, v22, v16
	v_add_f32_e32 v17, 1.0, v21
	v_div_scale_f32 v18, s[8:9], v17, v17, v19
	v_rcp_f32_e32 v20, v18
	v_med3_f32 v16, v16, s57, v194
	v_cvt_f16_f32_e32 v16, v16
	v_fma_f32 v21, -v18, v20, 1.0
	v_fmac_f32_e32 v20, v21, v20
	v_div_scale_f32 v21, vcc, v19, v17, v19
	v_mul_f32_e32 v22, v21, v20
	v_fma_f32 v24, -v18, v22, v21
	v_fmac_f32_e32 v22, v24, v20
	v_fma_f32 v18, -v18, v22, v21
	v_div_fmas_f32 v18, v18, v20, v22
	v_div_fixup_f32 v17, v18, v17, v19
	v_mul_f32_e32 v18, 0xbfb8aa3b, v8
	v_exp_f32_e32 v18, v18
	v_mul_f32_e32 v17, v23, v17
	v_med3_f32 v17, v17, s57, v194
	v_cvt_f16_f32_e32 v17, v17
	v_add_f32_e32 v18, 1.0, v18
	v_div_scale_f32 v19, s[8:9], v18, v18, v8
	v_rcp_f32_e32 v20, v19
	global_store_short v[28:29], v16, off offset:32
	global_store_short v[26:27], v17, off offset:32
	v_or_b32_e32 v16, 48, v50
	v_fma_f32 v17, -v19, v20, 1.0
	v_fmac_f32_e32 v20, v17, v20
	v_div_scale_f32 v17, vcc, v8, v18, v8
	v_mul_f32_e32 v21, v17, v20
	v_fma_f32 v22, -v19, v21, v17
	v_fmac_f32_e32 v21, v22, v20
	v_fma_f32 v17, -v19, v21, v17
	v_div_fmas_f32 v17, v17, v20, v21
	v_div_fixup_f32 v8, v17, v18, v8
	v_mul_f32_e32 v17, 0xbfb8aa3b, v9
	v_exp_f32_e32 v17, v17
	v_mul_f32_e32 v8, v12, v8
	v_med3_f32 v8, v8, s57, v194
	v_cvt_f16_f32_e32 v8, v8
	v_add_f32_e32 v12, 1.0, v17
	v_div_scale_f32 v18, s[8:9], v12, v12, v9
	v_rcp_f32_e32 v19, v18
	v_mad_i64_i32 v[16:17], s[8:9], v16, s64, v[48:49]
	global_store_short v[16:17], v8, off
	v_fma_f32 v20, -v18, v19, 1.0
	v_fmac_f32_e32 v19, v20, v19
	v_div_scale_f32 v20, vcc, v9, v12, v9
	v_mul_f32_e32 v21, v20, v19
	v_fma_f32 v22, -v18, v21, v20
	v_fmac_f32_e32 v21, v22, v19
	v_fma_f32 v18, -v18, v21, v20
	v_div_fmas_f32 v18, v18, v19, v21
	v_div_fixup_f32 v9, v18, v12, v9
	v_mul_f32_e32 v12, 0xbfb8aa3b, v10
	v_exp_f32_e32 v12, v12
	v_mul_f32_e32 v9, v13, v9
	v_med3_f32 v9, v9, s57, v194
	v_cvt_f16_f32_e32 v13, v9
	v_add_f32_e32 v12, 1.0, v12
	v_div_scale_f32 v18, s[8:9], v12, v12, v10
	v_rcp_f32_e32 v19, v18
	v_or_b32_e32 v8, 49, v50
	v_mad_i64_i32 v[8:9], s[8:9], v8, s64, v[48:49]
	v_fma_f32 v20, -v18, v19, 1.0
	v_fmac_f32_e32 v19, v20, v19
	v_div_scale_f32 v20, vcc, v10, v12, v10
	v_mul_f32_e32 v21, v20, v19
	v_fma_f32 v22, -v18, v21, v20
	v_fmac_f32_e32 v21, v22, v19
	v_fma_f32 v18, -v18, v21, v20
	v_div_fmas_f32 v18, v18, v19, v21
	v_div_fixup_f32 v10, v18, v12, v10
	v_mul_f32_e32 v12, 0xbfb8aa3b, v11
	v_exp_f32_e32 v12, v12
	v_mul_f32_e32 v10, v14, v10
	v_med3_f32 v10, v10, s57, v194
	v_cvt_f16_f32_e32 v10, v10
	v_add_f32_e32 v14, 1.0, v12
	v_div_scale_f32 v18, s[8:9], v14, v14, v11
	v_rcp_f32_e32 v19, v18
	global_store_short v[8:9], v13, off
	v_or_b32_e32 v13, 50, v50
	v_mad_i64_i32 v[12:13], s[8:9], v13, s64, v[48:49]
	v_fma_f32 v20, -v18, v19, 1.0
	v_fmac_f32_e32 v19, v20, v19
	v_div_scale_f32 v20, vcc, v11, v14, v11
	v_mul_f32_e32 v21, v20, v19
	v_fma_f32 v22, -v18, v21, v20
	v_fmac_f32_e32 v21, v22, v19
	v_fma_f32 v18, -v18, v21, v20
	v_div_fmas_f32 v18, v18, v19, v21
	v_mul_f32_e32 v19, 0xbfb8aa3b, v0
	v_exp_f32_e32 v19, v19
	v_div_fixup_f32 v11, v18, v14, v11
	v_mul_f32_e32 v11, v15, v11
	v_med3_f32 v11, v11, s57, v194
	v_add_f32_e32 v14, 1.0, v19
	v_div_scale_f32 v15, s[8:9], v14, v14, v0
	v_rcp_f32_e32 v18, v15
	v_cvt_f16_f32_e32 v19, v11
	global_store_short v[12:13], v10, off
	v_or_b32_e32 v10, 51, v50
	v_fma_f32 v20, -v15, v18, 1.0
	v_fmac_f32_e32 v18, v20, v18
	v_div_scale_f32 v20, vcc, v0, v14, v0
	v_mul_f32_e32 v21, v20, v18
	v_fma_f32 v22, -v15, v21, v20
	v_fmac_f32_e32 v21, v22, v18
	v_fma_f32 v15, -v15, v21, v20
	v_mul_f32_e32 v20, 0xbfb8aa3b, v1
	v_exp_f32_e32 v20, v20
	v_div_fmas_f32 v15, v15, v18, v21
	v_div_fixup_f32 v0, v15, v14, v0
	v_mul_f32_e32 v0, v4, v0
	v_add_f32_e32 v14, 1.0, v20
	v_div_scale_f32 v15, s[8:9], v14, v14, v1
	v_rcp_f32_e32 v18, v15
	v_med3_f32 v0, v0, s57, v194
	v_cvt_f16_f32_e32 v0, v0
	v_mad_i64_i32 v[10:11], s[8:9], v10, s64, v[48:49]
	v_fma_f32 v4, -v15, v18, 1.0
	v_fmac_f32_e32 v18, v4, v18
	v_div_scale_f32 v4, vcc, v1, v14, v1
	v_mul_f32_e32 v20, v4, v18
	v_fma_f32 v21, -v15, v20, v4
	v_fmac_f32_e32 v20, v21, v18
	v_fma_f32 v4, -v15, v20, v4
	v_div_fmas_f32 v4, v4, v18, v20
	v_div_fixup_f32 v1, v4, v14, v1
	v_mul_f32_e32 v4, 0xbfb8aa3b, v2
	v_exp_f32_e32 v4, v4
	v_mul_f32_e32 v1, v5, v1
	v_med3_f32 v1, v1, s57, v194
	v_cvt_f16_f32_e32 v1, v1
	v_add_f32_e32 v4, 1.0, v4
	v_div_scale_f32 v5, s[8:9], v4, v4, v2
	v_rcp_f32_e32 v14, v5
	global_store_short v[10:11], v19, off
	global_store_short v[16:17], v0, off offset:32
	global_store_short v[8:9], v1, off offset:32
	v_fma_f32 v0, -v5, v14, 1.0
	v_fmac_f32_e32 v14, v0, v14
	v_div_scale_f32 v0, vcc, v2, v4, v2
	v_mul_f32_e32 v1, v0, v14
	v_fma_f32 v8, -v5, v1, v0
	v_fmac_f32_e32 v1, v8, v14
	v_fma_f32 v0, -v5, v1, v0
	v_mul_f32_e32 v5, 0xbfb8aa3b, v3
	v_exp_f32_e32 v5, v5
	v_div_fmas_f32 v0, v0, v14, v1
	v_div_fixup_f32 v0, v0, v4, v2
	v_mul_f32_e32 v0, v6, v0
	v_add_f32_e32 v1, 1.0, v5
	v_div_scale_f32 v2, s[8:9], v1, v1, v3
	v_rcp_f32_e32 v4, v2
	v_med3_f32 v0, v0, s57, v194
	v_cvt_f16_f32_e32 v0, v0
	v_fma_f32 v5, -v2, v4, 1.0
	v_fmac_f32_e32 v4, v5, v4
	v_div_scale_f32 v5, vcc, v3, v1, v3
	v_mul_f32_e32 v6, v5, v4
	v_fma_f32 v8, -v2, v6, v5
	v_fmac_f32_e32 v6, v8, v4
	v_fma_f32 v2, -v2, v6, v5
	v_div_fmas_f32 v2, v2, v4, v6
	v_div_fixup_f32 v1, v2, v1, v3
	v_mul_f32_e32 v1, v7, v1
	v_med3_f32 v1, v1, s57, v194
	v_cvt_f16_f32_e32 v1, v1
	global_store_short v[12:13], v0, off offset:32
	global_store_short v[10:11], v1, off offset:32
	s_cbranch_scc0 .LBB0_136

.Lmoba_new:
	v_readfirstlane_b32 s14, v68
	v_readfirstlane_b32 s15, v69
	v_readfirstlane_b32 s16, v78
	v_readfirstlane_b32 s17, v79
	v_mov_b32_e32 v166, 0xff800000
	v_mov_b32_e32 v167, 0x3e38aa3b
	v_add_u32_e32 v156, v64, v65
	v_lshlrev_b32_e32 v157, 2, v156
	v_add_u32_e32 v157, 0x11900, v157
	ds_read_b32 v77, v157
	s_lshl_b32 s23, s49, 6
	s_sub_u32 s23, s23, 64
	v_add_u32_e32 v88, s23, v156
	v_sub_u32_e32 v88, v88, v67
	v_mul_u32_u24_e32 v151, 0x1900, v60
	v_add_u32_e32 v151, v151, v112
	v_add_u32_e32 v151, 0xf00, v151
	v_add_u32_e32 v152, 0x32000, v151
	v_add_u32_e32 v153, v70, v112
	v_add_u32_e32 v154, v74, v112
	v_mov_b32_e32 v148, v93
	v_lshlrev_b32_e32 v158, 1, v67
	v_sub_u32_e32 v158, v93, v158
	v_add_u32_e32 v144, 0x2400, v158
	v_add_u32_e32 v145, 0x2d00, v158
	v_add_u32_e32 v146, 0x3600, v158
	v_add_u32_e32 v147, 0x3f00, v158
	v_lshl_add_u32 v149, v61, 1, v112
	v_lshl_add_u32 v150, v63, 1, v112
	v_add_u32_e32 v149, 0x4800, v149
	v_add_u32_e32 v150, 0x4800, v150
	v_mul_u32_u24_e32 v155, 0x1900, v156
	v_lshl_add_u32 v155, v67, 1, v155
	s_mul_i32 s23, s80, 0x1900
	s_add_u32 s23, s23, s20
	s_add_u32 s23, s23, 0x1400
	s_add_u32 s76, s30, s23
	s_addc_u32 s77, s31, 0
	s_lshl_b32 s23, 1, s21
	s_or_b32 s12, s48, s23
	s_lshl_b32 s23, 2, s21
	s_sub_u32 s23, s23, 1
	s_and_b32 s12, s12, s23
	s_mov_b32 s9, 0
	s_mov_b32 s13, 0x4800
	v_mov_b32_e32 v72, v166
	v_mov_b32_e32 v73, 0
	v_mov_b32_e32 v28, 0
	v_mov_b32_e32 v29, 0
	v_mov_b32_e32 v30, 0
	v_mov_b32_e32 v31, 0
	v_mov_b32_e32 v32, 0
	v_mov_b32_e32 v33, 0
	v_mov_b32_e32 v34, 0
	v_mov_b32_e32 v35, 0
	v_mov_b32_e32 v36, 0
	v_mov_b32_e32 v37, 0
	v_mov_b32_e32 v38, 0
	v_mov_b32_e32 v39, 0
	v_mov_b32_e32 v40, 0
	v_mov_b32_e32 v41, 0
	v_mov_b32_e32 v42, 0
	v_mov_b32_e32 v43, 0
	s_waitcnt lgkmcnt(0)
	s_cmp_eq_u32 s8, s21
	s_cbranch_scc1 .Lmoba_own_top
.Lmoba_past_top:
	ds_read_b128 v[44:47], v148 offset:0
	ds_read_b128 v[48:51], v148 offset:64
	ds_read_b128 v[52:55], v148 offset:2304
	ds_read_b128 v[56:59], v148 offset:2368
	ds_read_b128 v[96:99], v148 offset:4608
	ds_read_b128 v[100:103], v148 offset:4672
	ds_read_b128 v[104:107], v148 offset:6912
	ds_read_b128 v[168:171], v148 offset:6976
	s_cmp_eq_u32 s8, s21
	s_cselect_b32 s23, s49, 4
	s_add_u32 s11, s9, 1
	s_mov_b32 s10, s8
	s_cmp_lt_u32 s11, s23
	s_cbranch_scc1 .Lmoba_past_have
	s_lshl_b32 s23, 2, s8
	s_sub_u32 s23, s23, 1
	s_andn2_b32 s23, s12, s23
	s_cmp_eq_u32 s23, 0
	s_cbranch_scc1 .Lmoba_past_nonext
	s_ff1_i32_b32 s10, s23
	s_mov_b32 s11, 0
.Lmoba_past_have:
	s_lshl_b32 s23, s10, 8
	s_lshl_b32 s36, s11, 6
	s_add_u32 s23, s23, s36
	s_mul_i32 s36, s23, 0x1900
	s_add_u32 s2, s14, s36
	s_addc_u32 s3, s15, 0
	s_lshl_b32 s23, s23, 1
	s_add_u32 s4, s16, s23
	s_addc_u32 s5, s17, 0
	s_mov_b32 s37, 1
	global_load_dwordx4 v[80:83], v151, s[2:3]
	global_load_dwordx4 v[84:87], v153, s[4:5]
	global_load_dwordx4 v[116:119], v152, s[2:3]
	global_load_dwordx4 v[120:123], v154, s[4:5]
	s_branch .Lmoba_past_qk
.Lmoba_past_nonext:
	s_mov_b32 s37, 0
.Lmoba_past_qk:
	s_waitcnt lgkmcnt(6)
	v_mfma_f32_16x16x32_f16 v[12:15], v[44:47], v[0:3], 0
	s_waitcnt lgkmcnt(4)
	v_mfma_f32_16x16x32_f16 v[16:19], v[52:55], v[0:3], 0
	s_waitcnt lgkmcnt(2)
	v_mfma_f32_16x16x32_f16 v[20:23], v[96:99], v[0:3], 0
	s_waitcnt lgkmcnt(0)
	v_mfma_f32_16x16x32_f16 v[24:27], v[104:107], v[0:3], 0
	v_mfma_f32_16x16x32_f16 v[12:15], v[48:51], v[4:7], v[12:15]
	v_mfma_f32_16x16x32_f16 v[16:19], v[56:59], v[4:7], v[16:19]
	v_mfma_f32_16x16x32_f16 v[20:23], v[100:103], v[4:7], v[20:23]
	v_mfma_f32_16x16x32_f16 v[24:27], v[168:171], v[4:7], v[24:27]
	ds_read2_b64 v[44:47], v144 offset0:0 offset1:4
	ds_read2_b64 v[48:51], v144 offset0:8 offset1:12
	ds_read2_b64 v[52:55], v145 offset0:0 offset1:4
	ds_read2_b64 v[56:59], v145 offset0:8 offset1:12
	ds_read2_b64 v[96:99], v146 offset0:0 offset1:4
	ds_read2_b64 v[100:103], v146 offset0:8 offset1:12
	ds_read2_b64 v[104:107], v147 offset0:0 offset1:4
	ds_read2_b64 v[168:171], v147 offset0:8 offset1:12
	s_lshl_b32 s23, 1, s8
	v_and_b32_e32 v156, s23, v77
	v_cmp_ne_u32_e64 s[98:99], 0, v156
	s_nop 3
	v_max3_f32 v157, v12, v13, v14
	v_max3_f32 v158, v15, v16, v17
	v_max3_f32 v159, v18, v19, v20
	v_max3_f32 v160, v21, v22, v23
	v_max3_f32 v161, v24, v25, v26
	v_max3_f32 v157, v157, v158, v27
	v_max3_f32 v157, v157, v159, v160
	v_max_f32_e32 v157, v157, v161
	v_cndmask_b32_e64 v157, v166, v157, s[98:99]
	v_mov_b32_e32 v158, v157
	s_nop 1
	v_permlane16_swap_b32_e32 v157, v158
	v_max_f32_e32 v157, v157, v158
	v_mov_b32_e32 v158, v157
	s_nop 1
	v_permlane32_swap_b32_e32 v157, v158
	v_max_f32_e32 v157, v157, v158
	v_max_f32_e32 v158, v72, v157
	v_cmp_eq_f32_e64 s[100:101], v158, v166
	v_sub_f32_e32 v160, v72, v158
	v_mov_b32_e32 v162, v72
	v_mov_b32_e32 v72, v158
	v_cndmask_b32_e64 v159, v158, 0, s[100:101]
	v_sub_f32_e32 v160, v162, v159
	v_mul_f32_e32 v160, v167, v160
	v_exp_f32_e32 v160, v160
	v_mul_f32_e64 v161, -v159, v167
	v_cndmask_b32_e64 v161, v166, v161, s[98:99]
	v_fma_f32 v12, v12, v167, v161
	v_fma_f32 v13, v13, v167, v161
	v_fma_f32 v14, v14, v167, v161
	v_fma_f32 v15, v15, v167, v161
	v_fma_f32 v16, v16, v167, v161
	v_fma_f32 v17, v17, v167, v161
	v_fma_f32 v18, v18, v167, v161
	v_fma_f32 v19, v19, v167, v161
	v_fma_f32 v20, v20, v167, v161
	v_fma_f32 v21, v21, v167, v161
	v_fma_f32 v22, v22, v167, v161
	v_fma_f32 v23, v23, v167, v161
	v_fma_f32 v24, v24, v167, v161
	v_fma_f32 v25, v25, v167, v161
	v_fma_f32 v26, v26, v167, v161
	v_fma_f32 v27, v27, v167, v161
	v_exp_f32_e32 v12, v12
	v_exp_f32_e32 v13, v13
	v_exp_f32_e32 v14, v14
	v_exp_f32_e32 v15, v15
	v_exp_f32_e32 v16, v16
	v_exp_f32_e32 v17, v17
	v_exp_f32_e32 v18, v18
	v_exp_f32_e32 v19, v19
	v_exp_f32_e32 v20, v20
	v_exp_f32_e32 v21, v21
	v_exp_f32_e32 v22, v22
	v_exp_f32_e32 v23, v23
	v_exp_f32_e32 v24, v24
	v_exp_f32_e32 v25, v25
	v_exp_f32_e32 v26, v26
	v_exp_f32_e32 v27, v27
	v_mul_f32_e32 v28, v28, v160
	v_mul_f32_e32 v29, v29, v160
	v_mul_f32_e32 v30, v30, v160
	v_mul_f32_e32 v31, v31, v160
	v_mul_f32_e32 v32, v32, v160
	v_mul_f32_e32 v33, v33, v160
	v_mul_f32_e32 v34, v34, v160
	v_mul_f32_e32 v35, v35, v160
	v_mul_f32_e32 v36, v36, v160
	v_mul_f32_e32 v37, v37, v160
	v_mul_f32_e32 v38, v38, v160
	v_mul_f32_e32 v39, v39, v160
	v_mul_f32_e32 v40, v40, v160
	v_mul_f32_e32 v41, v41, v160
	v_mul_f32_e32 v42, v42, v160
	v_mul_f32_e32 v43, v43, v160
	v_add_f32_e32 v157, v12, v13
	v_add_f32_e32 v157, v157, v14
	v_add_f32_e32 v157, v157, v15
	v_add_f32_e32 v157, v157, v16
	v_add_f32_e32 v157, v157, v17
	v_add_f32_e32 v157, v157, v18
	v_add_f32_e32 v157, v157, v19
	v_add_f32_e32 v157, v157, v20
	v_add_f32_e32 v157, v157, v21
	v_add_f32_e32 v157, v157, v22
	v_add_f32_e32 v157, v157, v23
	v_add_f32_e32 v157, v157, v24
	v_add_f32_e32 v157, v157, v25
	v_add_f32_e32 v157, v157, v26
	v_add_f32_e32 v157, v157, v27
	v_mov_b32_e32 v158, v157
	s_nop 1
	v_permlane16_swap_b32_e32 v157, v158
	v_add_f32_e32 v157, v157, v158
	v_mov_b32_e32 v158, v157
	s_nop 1
	v_permlane32_swap_b32_e32 v157, v158
	v_add_f32_e32 v157, v157, v158
	v_fma_f32 v73, v73, v160, v157
	v_cvt_pk_f16_f32 v136, v12, v13
	v_cvt_pk_f16_f32 v137, v14, v15
	v_cvt_pk_f16_f32 v138, v16, v17
	v_cvt_pk_f16_f32 v139, v18, v19
	v_cvt_pk_f16_f32 v140, v20, v21
	v_cvt_pk_f16_f32 v141, v22, v23
	v_cvt_pk_f16_f32 v142, v24, v25
	v_cvt_pk_f16_f32 v143, v26, v27
	s_waitcnt lgkmcnt(0)
	s_nop 1
	v_mfma_f32_16x16x32_f16 v[28:31], v[44:47], v[136:139], v[28:31]
	v_mfma_f32_16x16x32_f16 v[28:31], v[48:51], v[140:143], v[28:31]
	v_mfma_f32_16x16x32_f16 v[32:35], v[52:55], v[136:139], v[32:35]
	v_mfma_f32_16x16x32_f16 v[32:35], v[56:59], v[140:143], v[32:35]
	v_mfma_f32_16x16x32_f16 v[36:39], v[96:99], v[136:139], v[36:39]
	v_mfma_f32_16x16x32_f16 v[36:39], v[100:103], v[140:143], v[36:39]
	v_mfma_f32_16x16x32_f16 v[40:43], v[104:107], v[136:139], v[40:43]
	v_mfma_f32_16x16x32_f16 v[40:43], v[168:171], v[140:143], v[40:43]
	s_cmp_eq_u32 s37, 0
	s_cbranch_scc1 .Lmoba_done
	s_waitcnt vmcnt(0)
	ds_write_b128 v149, v[80:83]
	ds_write_b128 v149, v[84:87] offset:9216
	ds_write_b128 v150, v[116:119]
	ds_write_b128 v150, v[120:123] offset:9216
	v_add_u32_e32 v148, s13, v148
	v_add_u32_e32 v144, s13, v144
	v_add_u32_e32 v145, s13, v145
	v_add_u32_e32 v146, s13, v146
	v_add_u32_e32 v147, s13, v147
	v_subrev_u32_e32 v149, s13, v149
	v_subrev_u32_e32 v150, s13, v150
	s_sub_u32 s13, 0, s13
	s_mov_b32 s8, s10
	s_mov_b32 s9, s11
	s_waitcnt lgkmcnt(0)
	s_barrier
	s_cmp_eq_u32 s8, s21
	s_cbranch_scc0 .Lmoba_past_top
	s_branch .Lmoba_own_top

.Lmoba_own_qk:
	s_waitcnt lgkmcnt(6)
	v_mfma_f32_16x16x32_f16 v[12:15], v[44:47], v[0:3], 0
	s_waitcnt lgkmcnt(4)
	v_mfma_f32_16x16x32_f16 v[16:19], v[52:55], v[0:3], 0
	s_waitcnt lgkmcnt(2)
	v_mfma_f32_16x16x32_f16 v[20:23], v[96:99], v[0:3], 0
	s_waitcnt lgkmcnt(0)
	v_mfma_f32_16x16x32_f16 v[24:27], v[104:107], v[0:3], 0
	v_mfma_f32_16x16x32_f16 v[12:15], v[48:51], v[4:7], v[12:15]
	v_mfma_f32_16x16x32_f16 v[16:19], v[56:59], v[4:7], v[16:19]
	v_mfma_f32_16x16x32_f16 v[20:23], v[100:103], v[4:7], v[20:23]
	v_mfma_f32_16x16x32_f16 v[24:27], v[168:171], v[4:7], v[24:27]
	ds_read2_b64 v[44:47], v144 offset0:0 offset1:4
	ds_read2_b64 v[48:51], v144 offset0:8 offset1:12
	ds_read2_b64 v[52:55], v145 offset0:0 offset1:4
	ds_read2_b64 v[56:59], v145 offset0:8 offset1:12
	ds_read2_b64 v[96:99], v146 offset0:0 offset1:4
	ds_read2_b64 v[100:103], v146 offset0:8 offset1:12
	ds_read2_b64 v[104:107], v147 offset0:0 offset1:4
	ds_read2_b64 v[168:171], v147 offset0:8 offset1:12
	s_lshl_b32 s23, s9, 6
	v_subrev_u32_e32 v156, s23, v88
	s_nop 3
	v_cmp_le_i32_e64 s[98:99], 0, v156
	v_cmp_le_i32_e64 s[100:101], 1, v156
	v_cmp_le_i32_e64 s[66:67], 2, v156
	v_cmp_le_i32_e64 s[72:73], 3, v156
	v_cndmask_b32_e64 v12, v166, v12, s[98:99]
	v_cndmask_b32_e64 v13, v166, v13, s[100:101]
	v_cndmask_b32_e64 v14, v166, v14, s[66:67]
	v_cndmask_b32_e64 v15, v166, v15, s[72:73]
	v_cmp_le_i32_e64 s[98:99], 16, v156
	v_cmp_le_i32_e64 s[100:101], 17, v156
	v_cmp_le_i32_e64 s[66:67], 18, v156
	v_cmp_le_i32_e64 s[72:73], 19, v156
	v_cndmask_b32_e64 v16, v166, v16, s[98:99]
	v_cndmask_b32_e64 v17, v166, v17, s[100:101]
	v_cndmask_b32_e64 v18, v166, v18, s[66:67]
	v_cndmask_b32_e64 v19, v166, v19, s[72:73]
	v_cmp_le_i32_e64 s[98:99], 32, v156
	v_cmp_le_i32_e64 s[100:101], 33, v156
	v_cmp_le_i32_e64 s[66:67], 34, v156
	v_cmp_le_i32_e64 s[72:73], 35, v156
	v_cndmask_b32_e64 v20, v166, v20, s[98:99]
	v_cndmask_b32_e64 v21, v166, v21, s[100:101]
	v_cndmask_b32_e64 v22, v166, v22, s[66:67]
	v_cndmask_b32_e64 v23, v166, v23, s[72:73]
	v_cmp_le_i32_e64 s[98:99], 48, v156
	v_cmp_le_i32_e64 s[100:101], 49, v156
	v_cmp_le_i32_e64 s[66:67], 50, v156
	v_cmp_le_i32_e64 s[72:73], 51, v156
	v_cndmask_b32_e64 v24, v166, v24, s[98:99]
	v_cndmask_b32_e64 v25, v166, v25, s[100:101]
	v_cndmask_b32_e64 v26, v166, v26, s[66:67]
	v_cndmask_b32_e64 v27, v166, v27, s[72:73]
	v_max3_f32 v157, v12, v13, v14
	v_max3_f32 v158, v15, v16, v17
	v_max3_f32 v159, v18, v19, v20
	v_max3_f32 v160, v21, v22, v23
	v_max3_f32 v161, v24, v25, v26
	v_max3_f32 v157, v157, v158, v27
	v_max3_f32 v157, v157, v159, v160
	v_max_f32_e32 v157, v157, v161
	v_mov_b32_e32 v158, v157
	s_nop 1
	v_permlane16_swap_b32_e32 v157, v158
	v_max_f32_e32 v157, v157, v158
	v_mov_b32_e32 v158, v157
	s_nop 1
	v_permlane32_swap_b32_e32 v157, v158
	v_max_f32_e32 v157, v157, v158
	v_max_f32_e32 v158, v72, v157
	v_cmp_eq_f32_e64 s[100:101], v158, v166
	v_sub_f32_e32 v160, v72, v158
	v_mov_b32_e32 v162, v72
	v_mov_b32_e32 v72, v158
	v_cndmask_b32_e64 v159, v158, 0, s[100:101]
	v_sub_f32_e32 v160, v162, v159
	v_mul_f32_e32 v160, v167, v160
	v_exp_f32_e32 v160, v160
	v_mul_f32_e64 v161, -v159, v167
	v_fma_f32 v12, v12, v167, v161
	v_fma_f32 v13, v13, v167, v161
	v_fma_f32 v14, v14, v167, v161
	v_fma_f32 v15, v15, v167, v161
	v_fma_f32 v16, v16, v167, v161
	v_fma_f32 v17, v17, v167, v161
	v_fma_f32 v18, v18, v167, v161
	v_fma_f32 v19, v19, v167, v161
	v_fma_f32 v20, v20, v167, v161
	v_fma_f32 v21, v21, v167, v161
	v_fma_f32 v22, v22, v167, v161
	v_fma_f32 v23, v23, v167, v161
	v_fma_f32 v24, v24, v167, v161
	v_fma_f32 v25, v25, v167, v161
	v_fma_f32 v26, v26, v167, v161
	v_fma_f32 v27, v27, v167, v161
	v_exp_f32_e32 v12, v12
	v_exp_f32_e32 v13, v13
	v_exp_f32_e32 v14, v14
	v_exp_f32_e32 v15, v15
	v_exp_f32_e32 v16, v16
	v_exp_f32_e32 v17, v17
	v_exp_f32_e32 v18, v18
	v_exp_f32_e32 v19, v19
	v_exp_f32_e32 v20, v20
	v_exp_f32_e32 v21, v21
	v_exp_f32_e32 v22, v22
	v_exp_f32_e32 v23, v23
	v_exp_f32_e32 v24, v24
	v_exp_f32_e32 v25, v25
	v_exp_f32_e32 v26, v26
	v_exp_f32_e32 v27, v27
	v_mul_f32_e32 v28, v28, v160
	v_mul_f32_e32 v29, v29, v160
	v_mul_f32_e32 v30, v30, v160
	v_mul_f32_e32 v31, v31, v160
	v_mul_f32_e32 v32, v32, v160
	v_mul_f32_e32 v33, v33, v160
	v_mul_f32_e32 v34, v34, v160
	v_mul_f32_e32 v35, v35, v160
	v_mul_f32_e32 v36, v36, v160
	v_mul_f32_e32 v37, v37, v160
	v_mul_f32_e32 v38, v38, v160
	v_mul_f32_e32 v39, v39, v160
	v_mul_f32_e32 v40, v40, v160
	v_mul_f32_e32 v41, v41, v160
	v_mul_f32_e32 v42, v42, v160
	v_mul_f32_e32 v43, v43, v160
	v_add_f32_e32 v157, v12, v13
	v_add_f32_e32 v157, v157, v14
	v_add_f32_e32 v157, v157, v15
	v_add_f32_e32 v157, v157, v16
	v_add_f32_e32 v157, v157, v17
	v_add_f32_e32 v157, v157, v18
	v_add_f32_e32 v157, v157, v19
	v_add_f32_e32 v157, v157, v20
	v_add_f32_e32 v157, v157, v21
	v_add_f32_e32 v157, v157, v22
	v_add_f32_e32 v157, v157, v23
	v_add_f32_e32 v157, v157, v24
	v_add_f32_e32 v157, v157, v25
	v_add_f32_e32 v157, v157, v26
	v_add_f32_e32 v157, v157, v27
	v_mov_b32_e32 v158, v157
	s_nop 1
	v_permlane16_swap_b32_e32 v157, v158
	v_add_f32_e32 v157, v157, v158
	v_mov_b32_e32 v158, v157
	s_nop 1
	v_permlane32_swap_b32_e32 v157, v158
	v_add_f32_e32 v157, v157, v158
	v_fma_f32 v73, v73, v160, v157
	v_cvt_pk_f16_f32 v136, v12, v13
	v_cvt_pk_f16_f32 v137, v14, v15
	v_cvt_pk_f16_f32 v138, v16, v17
	v_cvt_pk_f16_f32 v139, v18, v19
	v_cvt_pk_f16_f32 v140, v20, v21
	v_cvt_pk_f16_f32 v141, v22, v23
	v_cvt_pk_f16_f32 v142, v24, v25
	v_cvt_pk_f16_f32 v143, v26, v27
	s_waitcnt lgkmcnt(0)
	s_nop 1
	v_mfma_f32_16x16x32_f16 v[28:31], v[44:47], v[136:139], v[28:31]
	v_mfma_f32_16x16x32_f16 v[28:31], v[48:51], v[140:143], v[28:31]
	v_mfma_f32_16x16x32_f16 v[32:35], v[52:55], v[136:139], v[32:35]
	v_mfma_f32_16x16x32_f16 v[32:35], v[56:59], v[140:143], v[32:35]
	v_mfma_f32_16x16x32_f16 v[36:39], v[96:99], v[136:139], v[36:39]
	v_mfma_f32_16x16x32_f16 v[36:39], v[100:103], v[140:143], v[36:39]
	v_mfma_f32_16x16x32_f16 v[40:43], v[104:107], v[136:139], v[40:43]
	v_mfma_f32_16x16x32_f16 v[40:43], v[168:171], v[140:143], v[40:43]
	s_cmp_eq_u32 s37, 0
	s_cbranch_scc1 .Lmoba_done
	s_waitcnt vmcnt(0)
	ds_write_b128 v149, v[80:83]
	ds_write_b128 v149, v[84:87] offset:9216
	ds_write_b128 v150, v[116:119]
	ds_write_b128 v150, v[120:123] offset:9216
	v_add_u32_e32 v148, s13, v148
	v_add_u32_e32 v144, s13, v144
	v_add_u32_e32 v145, s13, v145
	v_add_u32_e32 v146, s13, v146
	v_add_u32_e32 v147, s13, v147
	v_subrev_u32_e32 v149, s13, v149
	v_subrev_u32_e32 v150, s13, v150
	s_sub_u32 s13, 0, s13
	s_mov_b32 s8, s10
	s_mov_b32 s9, s11
	s_waitcnt lgkmcnt(0)
	s_barrier
	s_branch .Lmoba_own_top
.Lmoba_done:
	v_div_scale_f32 v156, s[98:99], v73, v73, 1.0
	v_rcp_f32_e32 v157, v156
	v_div_scale_f32 v158, vcc, 1.0, v73, 1.0
	v_fma_f32 v159, -v156, v157, 1.0
	v_fmac_f32_e32 v157, v159, v157
	v_mul_f32_e32 v159, v158, v157
	v_fma_f32 v160, -v156, v159, v158
	v_fmac_f32_e32 v159, v160, v157
	v_fma_f32 v156, -v156, v159, v158
	v_div_fmas_f32 v156, v156, v157, v159
	v_div_fixup_f32 v156, v156, v73, 1.0
	v_mul_f32_e32 v28, v28, v156
	v_med3_f32 v28, v28, s57, v194
	v_mul_f32_e32 v29, v29, v156
	v_med3_f32 v29, v29, s57, v194
	v_mul_f32_e32 v30, v30, v156
	v_med3_f32 v30, v30, s57, v194
	v_mul_f32_e32 v31, v31, v156
	v_med3_f32 v31, v31, s57, v194
	v_cvt_pk_f16_f32 v158, v28, v29
	v_cvt_pk_f16_f32 v159, v30, v31
	global_store_dwordx2 v155, v[158:159], s[76:77] offset:0
	s_nop 1
	v_mul_f32_e32 v32, v32, v156
	v_med3_f32 v32, v32, s57, v194
	v_mul_f32_e32 v33, v33, v156
	v_med3_f32 v33, v33, s57, v194
	v_mul_f32_e32 v34, v34, v156
	v_med3_f32 v34, v34, s57, v194
	v_mul_f32_e32 v35, v35, v156
	v_med3_f32 v35, v35, s57, v194
	v_cvt_pk_f16_f32 v158, v32, v33
	v_cvt_pk_f16_f32 v159, v34, v35
	global_store_dwordx2 v155, v[158:159], s[76:77] offset:32
	s_nop 1
	v_mul_f32_e32 v36, v36, v156
	v_med3_f32 v36, v36, s57, v194
	v_mul_f32_e32 v37, v37, v156
	v_med3_f32 v37, v37, s57, v194
	v_mul_f32_e32 v38, v38, v156
	v_med3_f32 v38, v38, s57, v194
	v_mul_f32_e32 v39, v39, v156
	v_med3_f32 v39, v39, s57, v194
	v_cvt_pk_f16_f32 v158, v36, v37
	v_cvt_pk_f16_f32 v159, v38, v39
	global_store_dwordx2 v155, v[158:159], s[76:77] offset:64
	s_nop 1
	v_mul_f32_e32 v40, v40, v156
	v_med3_f32 v40, v40, s57, v194
	v_mul_f32_e32 v41, v41, v156
	v_med3_f32 v41, v41, s57, v194
	v_mul_f32_e32 v42, v42, v156
	v_med3_f32 v42, v42, s57, v194
	v_mul_f32_e32 v43, v43, v156
	v_med3_f32 v43, v43, s57, v194
	v_cvt_pk_f16_f32 v158, v40, v41
	v_cvt_pk_f16_f32 v159, v42, v43
	global_store_dwordx2 v155, v[158:159], s[76:77] offset:96
	s_nop 1
	s_mov_b64 s[38:39], s[80:81]
	s_mov_b32 s21, s81
	s_movk_i32 s0, 0x1000
	s_mov_b64 s[2:3], 0x1400
	s_movk_i32 s48, 0x2000
	s_mov_b64 s[2:3], 0x2d00
	s_mov_b64 s[2:3], 0x4600
	s_mov_b64 s[2:3], 0x5f00
	s_movk_i32 s0, 0x5000
	v_readlane_b32 s66, v249, 32
	v_readlane_b32 s92, v249, 26
	v_readlane_b32 s86, v249, 28
	v_readlane_b32 s42, v249, 24
	s_mov_b64 s[8:9], 0
	s_mov_b32 s59, s74
	v_readlane_b32 s67, v249, 33
	v_readlane_b32 s93, v249, 27
	v_readlane_b32 s87, v249, 29
	s_mov_b32 s60, s75
	s_mov_b32 s62, s1
	s_mov_b32 s65, s33
	v_readlane_b32 s43, v249, 25
	v_readlane_b32 s33, v249, 30
	s_mov_b32 s46, 0x9000
	s_mov_b32 s49, 0x800000
	s_movk_i32 s44, 0x3c60
	s_movk_i32 s45, 0x104
	s_mov_b32 s68, 0x3fb8aa3b
	s_mov_b32 s69, 0xc2ce8ed0
	s_mov_b32 s74, 0x42b17218
	s_movk_i32 s70, 0x10ff
	s_mov_b64 s[72:73], 0x18c00080
	s_mov_b64 s[78:79], 0x1a200080
	s_mov_b64 s[80:81], 0x1180
	s_mov_b64 s[82:83], 0x1b4c0080
	v_readlane_b32 s71, v249, 40
	v_readlane_b32 s1, v249, 31
	s_branch .LBB0_535

.LBB0_634:
	s_barrier
	s_waitcnt lgkmcnt(0)
	v_readlane_b32 s8, v250, 17
	v_readlane_b32 s9, v250, 18
	s_lshl_b32 s12, s0, 7
	s_lshl_b32 s0, s11, 7
	v_lshrrev_b32_e32 v64, 4, v182
	v_xor_b32_e32 v64, v64, v182
	v_and_b32_e32 v64, 7, v64
	v_lshlrev_b32_e32 v64, 4, v64
	v_lshrrev_b32_e32 v65, 3, v182
	v_lshrrev_b32_e32 v68, 6, v182
	v_lshl_or_b32 v91, v65, 11, v64
	v_readfirstlane_b32 s5, v68
	v_add_u32_e32 v112, 0x10000, v91
	v_add_u32_e32 v148, 0x20000, v91
	v_add_u32_e32 v149, 0x30000, v91
	v_add3_u32 v64, v84, v85, v83
	v_add3_u32 v65, v81, v85, v83
	v_add3_u32 v66, v84, v82, v83
	v_add3_u32 v67, v81, v82, v83
	s_lshl_b32 s5, s5, 10
	s_lshl_b32 s4, s12, 11
	s_add_u32 s2, s40, s4
	s_addc_u32 s3, s41, 0
	s_lshl_b32 s4, s0, 11
	s_add_u32 s8, s8, s4
	s_addc_u32 s9, s9, 0
	s_mov_b32 m0, s5
	s_add_u32 s4, s5, 0x1000
	global_load_lds_dwordx4 v91, s[2:3]
	s_mov_b32 m0, s4
	s_add_u32 s4, s5, 0x2000
	global_load_lds_dwordx4 v112, s[2:3]
	s_mov_b32 m0, s4
	s_add_u32 s4, s5, 0x3000
	global_load_lds_dwordx4 v148, s[2:3]
	s_mov_b32 m0, s4
	s_add_u32 s4, s5, 0x4000
	global_load_lds_dwordx4 v149, s[2:3]
	s_mov_b32 m0, s4
	s_add_u32 s4, s5, 0x5000
	global_load_lds_dwordx4 v91, s[8:9]
	s_mov_b32 m0, s4
	s_add_u32 s4, s5, 0x6000
	global_load_lds_dwordx4 v112, s[8:9]
	s_mov_b32 m0, s4
	s_add_u32 s4, s5, 0x7000
	global_load_lds_dwordx4 v148, s[8:9]
	s_mov_b32 m0, s4
	s_add_u32 s13, s5, 0x8000
	global_load_lds_dwordx4 v149, s[8:9]
	s_movk_i32 s14, 15
	v_mov_b32_e32 v0, 0
	v_mov_b32_e32 v1, v0
	v_mov_b32_e32 v2, v0
	v_mov_b32_e32 v3, v0
	v_mov_b32_e32 v4, v0
	v_mov_b32_e32 v5, v0
	v_mov_b32_e32 v6, v0
	v_mov_b32_e32 v7, v0
	v_mov_b32_e32 v8, v0
	v_mov_b32_e32 v9, v0
	v_mov_b32_e32 v10, v0
	v_mov_b32_e32 v11, v0
	v_mov_b32_e32 v12, v0
	v_mov_b32_e32 v13, v0
	v_mov_b32_e32 v14, v0
	v_mov_b32_e32 v15, v0
	v_mov_b32_e32 v16, v0
	v_mov_b32_e32 v17, v0
	v_mov_b32_e32 v18, v0
	v_mov_b32_e32 v19, v0
	v_mov_b32_e32 v20, v0
	v_mov_b32_e32 v21, v0
	v_mov_b32_e32 v22, v0
	v_mov_b32_e32 v23, v0
	v_mov_b32_e32 v24, v0
	v_mov_b32_e32 v25, v0
	v_mov_b32_e32 v26, v0
	v_mov_b32_e32 v27, v0
	v_mov_b32_e32 v28, v0
	v_mov_b32_e32 v29, v0
	v_mov_b32_e32 v30, v0
	v_mov_b32_e32 v31, v0
	v_mov_b32_e32 v32, v0
	v_mov_b32_e32 v33, v0
	v_mov_b32_e32 v34, v0
	v_mov_b32_e32 v35, v0
	v_mov_b32_e32 v36, v0
	v_mov_b32_e32 v37, v0
	v_mov_b32_e32 v38, v0
	v_mov_b32_e32 v39, v0
	v_mov_b32_e32 v40, v0
	v_mov_b32_e32 v41, v0
	v_mov_b32_e32 v42, v0
	v_mov_b32_e32 v43, v0
	v_mov_b32_e32 v44, v0
	v_mov_b32_e32 v45, v0
	v_mov_b32_e32 v46, v0
	v_mov_b32_e32 v47, v0
	v_mov_b32_e32 v48, v0
	v_mov_b32_e32 v49, v0
	v_mov_b32_e32 v50, v0
	v_mov_b32_e32 v51, v0
	v_mov_b32_e32 v52, v0
	v_mov_b32_e32 v53, v0
	v_mov_b32_e32 v54, v0
	v_mov_b32_e32 v55, v0
	v_mov_b32_e32 v56, v0
	v_mov_b32_e32 v57, v0
	v_mov_b32_e32 v58, v0
	v_mov_b32_e32 v59, v0
	v_mov_b32_e32 v60, v0
	v_mov_b32_e32 v61, v0
	v_mov_b32_e32 v62, v0
	v_mov_b32_e32 v63, v0
.Lgk_sw2:
	s_waitcnt vmcnt(0)
	s_barrier
	ds_read_b128 v[96:99], v66 offset:16384
	ds_read_b128 v[68:71], v64
	ds_read_b128 v[100:103], v66 offset:18432
	ds_read_b128 v[104:107], v66 offset:20480
	ds_read_b128 v[108:111], v66 offset:22528
	ds_read_b128 v[72:75], v64 offset:2048
	ds_read_b128 v[76:79], v64 offset:4096
	ds_read_b128 v[92:95], v64 offset:6144
	s_add_u32 s2, s2, 0x80
	s_addc_u32 s3, s3, 0
	s_add_u32 s8, s8, 0x80
	s_addc_u32 s9, s9, 0
	s_mov_b32 m0, s13
	s_add_u32 s4, s13, 0x1000
	global_load_lds_dwordx4 v91, s[2:3]
	s_mov_b32 m0, s4
	s_add_u32 s4, s13, 0x2000
	global_load_lds_dwordx4 v112, s[2:3]
	s_mov_b32 m0, s4
	s_add_u32 s4, s13, 0x3000
	global_load_lds_dwordx4 v148, s[2:3]
	s_mov_b32 m0, s4
	s_add_u32 s4, s13, 0x4000
	global_load_lds_dwordx4 v149, s[2:3]
	s_mov_b32 m0, s4
	s_add_u32 s4, s13, 0x5000
	global_load_lds_dwordx4 v91, s[8:9]
	s_mov_b32 m0, s4
	s_add_u32 s4, s13, 0x6000
	global_load_lds_dwordx4 v112, s[8:9]
	s_mov_b32 m0, s4
	s_add_u32 s4, s13, 0x7000
	global_load_lds_dwordx4 v148, s[8:9]
	s_mov_b32 m0, s4
	s_sub_u32 s14, s14, 1
	global_load_lds_dwordx4 v149, s[8:9]
	s_xor_b32 s13, s13, 0x8000
	s_waitcnt lgkmcnt(3)
	v_mfma_f32_16x16x32_f16 v[60:63], v[68:71], v[96:99], v[60:63]
	v_mfma_f32_16x16x32_f16 v[56:59], v[68:71], v[100:103], v[56:59]
	v_mfma_f32_16x16x32_f16 v[52:55], v[68:71], v[104:107], v[52:55]
	v_mfma_f32_16x16x32_f16 v[48:51], v[68:71], v[108:111], v[48:51]
	ds_read_b128 v[132:135], v67 offset:16384
	ds_read_b128 v[116:119], v65
	s_waitcnt lgkmcnt(4)
	v_mfma_f32_16x16x32_f16 v[44:47], v[72:75], v[96:99], v[44:47]
	v_mfma_f32_16x16x32_f16 v[40:43], v[72:75], v[100:103], v[40:43]
	v_mfma_f32_16x16x32_f16 v[36:39], v[72:75], v[104:107], v[36:39]
	v_mfma_f32_16x16x32_f16 v[32:35], v[72:75], v[108:111], v[32:35]
	ds_read_b128 v[136:139], v67 offset:18432
	ds_read_b128 v[140:143], v67 offset:20480
	s_waitcnt lgkmcnt(5)
	v_mfma_f32_16x16x32_f16 v[28:31], v[76:79], v[96:99], v[28:31]
	v_mfma_f32_16x16x32_f16 v[24:27], v[76:79], v[100:103], v[24:27]
	v_mfma_f32_16x16x32_f16 v[20:23], v[76:79], v[104:107], v[20:23]
	v_mfma_f32_16x16x32_f16 v[16:19], v[76:79], v[108:111], v[16:19]
	ds_read_b128 v[144:147], v67 offset:22528
	ds_read_b128 v[120:123], v65 offset:2048
	s_waitcnt lgkmcnt(6)
	v_mfma_f32_16x16x32_f16 v[12:15], v[92:95], v[96:99], v[12:15]
	v_mfma_f32_16x16x32_f16 v[8:11], v[92:95], v[100:103], v[8:11]
	v_mfma_f32_16x16x32_f16 v[4:7], v[92:95], v[104:107], v[4:7]
	v_mfma_f32_16x16x32_f16 v[0:3], v[92:95], v[108:111], v[0:3]
	ds_read_b128 v[124:127], v65 offset:4096
	ds_read_b128 v[128:131], v65 offset:6144
	v_xor_b32_e32 v64, 0x8000, v64
	v_xor_b32_e32 v66, 0x8000, v66
	s_waitcnt lgkmcnt(3)
	v_mfma_f32_16x16x32_f16 v[60:63], v[116:119], v[132:135], v[60:63]
	v_mfma_f32_16x16x32_f16 v[56:59], v[116:119], v[136:139], v[56:59]
	v_mfma_f32_16x16x32_f16 v[52:55], v[116:119], v[140:143], v[52:55]
	v_mfma_f32_16x16x32_f16 v[48:51], v[116:119], v[144:147], v[48:51]
	v_xor_b32_e32 v65, 0x8000, v65
	v_xor_b32_e32 v67, 0x8000, v67
	s_waitcnt lgkmcnt(2)
	v_mfma_f32_16x16x32_f16 v[44:47], v[120:123], v[132:135], v[44:47]
	v_mfma_f32_16x16x32_f16 v[40:43], v[120:123], v[136:139], v[40:43]
	v_mfma_f32_16x16x32_f16 v[36:39], v[120:123], v[140:143], v[36:39]
	v_mfma_f32_16x16x32_f16 v[32:35], v[120:123], v[144:147], v[32:35]
	s_waitcnt lgkmcnt(1)
	v_mfma_f32_16x16x32_f16 v[28:31], v[124:127], v[132:135], v[28:31]
	v_mfma_f32_16x16x32_f16 v[24:27], v[124:127], v[136:139], v[24:27]
	v_mfma_f32_16x16x32_f16 v[20:23], v[124:127], v[140:143], v[20:23]
	v_mfma_f32_16x16x32_f16 v[16:19], v[124:127], v[144:147], v[16:19]
	s_cmp_lg_u32 s14, 0
	s_waitcnt lgkmcnt(0)
	v_mfma_f32_16x16x32_f16 v[12:15], v[128:131], v[132:135], v[12:15]
	v_mfma_f32_16x16x32_f16 v[8:11], v[128:131], v[136:139], v[8:11]
	v_mfma_f32_16x16x32_f16 v[4:7], v[128:131], v[140:143], v[4:7]
	v_mfma_f32_16x16x32_f16 v[0:3], v[128:131], v[144:147], v[0:3]
	s_cbranch_scc1 .Lgk_sw2
	s_waitcnt vmcnt(0)
	s_barrier
	ds_read_b128 v[64:67], v90 offset:32768
	ds_read_b128 v[68:71], v89 offset:49152
	ds_read_b128 v[72:75], v89 offset:51200
	ds_read_b128 v[76:79], v89 offset:53248
	ds_read_b128 v[92:95], v89 offset:55296
	ds_read_b128 v[96:99], v90 offset:34816
	ds_read_b128 v[100:103], v88 offset:32768
	ds_read_b128 v[104:107], v88 offset:34816
	ds_read_b128 v[108:111], v87 offset:51200
	ds_read_b128 v[116:119], v87 offset:49152
	s_waitcnt lgkmcnt(8)
	v_mfma_f32_16x16x32_f16 v[60:63], v[64:67], v[68:71], v[60:63]
	ds_read_b128 v[124:127], v87 offset:55296
	ds_read_b128 v[128:131], v87 offset:53248
	ds_read_b128 v[132:135], v88 offset:38912
	ds_read_b128 v[136:139], v88 offset:36864
	s_add_i32 s10, s10, s60
	s_cmp_ge_i32 s10, s62
	s_waitcnt lgkmcnt(4)
	v_mfma_f32_16x16x32_f16 v[60:63], v[100:103], v[116:119], v[60:63]
	v_mfma_f32_16x16x32_f16 v[56:59], v[64:67], v[72:75], v[56:59]
	v_mfma_f32_16x16x32_f16 v[52:55], v[64:67], v[76:79], v[52:55]
	v_mfma_f32_16x16x32_f16 v[64:67], v[64:67], v[92:95], v[48:51]
	v_mfma_f32_16x16x32_f16 v[120:123], v[96:99], v[72:75], v[40:43]
	s_nop 2
	ds_read_b128 v[40:43], v90 offset:38912
	ds_read_b128 v[140:143], v90 offset:36864
	v_mul_f32_e32 v48, 0xbfb8aa3b, v60
	v_exp_f32_e32 v49, v48
	s_waitcnt lgkmcnt(0)
	v_mfma_f32_16x16x32_f16 v[28:31], v[140:143], v[68:71], v[28:31]
	v_add_f32_e32 v51, 1.0, v49
	v_lshl_or_b32 v48, s11, 6, v86
	v_add_u32_e32 v50, s12, v80
	v_mfma_f32_16x16x32_f16 v[144:147], v[140:143], v[72:75], v[24:27]
	v_ashrrev_i32_e32 v49, 31, v48
	v_lshl_add_u64 v[48:49], v[48:49], 1, s[30:31]
	v_mad_i64_i32 v[148:149], s[2:3], v50, s64, v[48:49]
	v_mfma_f32_16x16x32_f16 v[20:23], v[140:143], v[76:79], v[20:23]
	v_div_scale_f32 v24, vcc, v60, v51, v60
	v_mfma_f32_16x16x32_f16 v[140:143], v[140:143], v[92:95], v[16:19]
	s_nop 2
	v_mul_f32_e32 v17, 0xbfb8aa3b, v61
	v_mfma_f32_16x16x32_f16 v[44:47], v[96:99], v[68:71], v[44:47]
	v_exp_f32_e32 v17, v17
	v_mfma_f32_16x16x32_f16 v[36:39], v[96:99], v[76:79], v[36:39]
	v_mfma_f32_16x16x32_f16 v[96:99], v[96:99], v[92:95], v[32:35]
	s_nop 2
	v_div_scale_f32 v32, s[2:3], v51, v51, v60
	v_rcp_f32_e32 v33, v32
	v_mfma_f32_16x16x32_f16 v[12:15], v[40:43], v[68:71], v[12:15]
	v_fma_f32 v34, -v32, v33, 1.0
	v_mfma_f32_16x16x32_f16 v[68:71], v[40:43], v[72:75], v[8:11]
	v_fmac_f32_e32 v33, v34, v33
	v_mul_f32_e32 v25, v24, v33
	v_fma_f32 v26, -v32, v25, v24
	v_add_f32_e32 v8, 1.0, v17
	v_div_scale_f32 v9, s[2:3], v8, v8, v61
	v_rcp_f32_e32 v10, v9
	v_fmac_f32_e32 v25, v26, v33
	v_fma_f32 v16, -v32, v25, v24
	v_mfma_f32_16x16x32_f16 v[72:75], v[40:43], v[92:95], v[0:3]
	v_div_fmas_f32 v16, v16, v33, v25
	v_div_fixup_f32 v16, v16, v51, v60
	v_or_b32_e32 v51, 2, v50
	v_fma_f32 v1, -v9, v10, 1.0
	v_fmac_f32_e32 v10, v1, v10
	v_div_scale_f32 v1, vcc, v61, v8, v61
	v_mul_f32_e32 v2, v1, v10
	v_fma_f32 v3, -v9, v2, v1
	v_fmac_f32_e32 v2, v3, v10
	v_fma_f32 v1, -v9, v2, v1
	v_div_fmas_f32 v1, v1, v10, v2
	v_mul_f32_e32 v2, 0xbfb8aa3b, v62
	v_mfma_f32_16x16x32_f16 v[52:55], v[100:103], v[128:131], v[52:55]
	v_exp_f32_e32 v2, v2
	v_or_b32_e32 v0, 1, v50
	v_div_fixup_f32 v1, v1, v8, v61
	v_mfma_f32_16x16x32_f16 v[4:7], v[40:43], v[76:79], v[4:7]
	v_mfma_f32_16x16x32_f16 v[56:59], v[100:103], v[108:111], v[56:59]
	s_nop 2
	v_mul_f32_e32 v16, v52, v16
	v_mul_f32_e32 v1, v53, v1
	v_mad_i64_i32 v[52:53], s[2:3], v0, s64, v[48:49]
	v_add_f32_e32 v0, 1.0, v2
	v_med3_f32 v1, v1, s57, v194
	v_div_scale_f32 v2, s[2:3], v0, v0, v62
	v_cvt_f16_f32_e32 v1, v1
	v_rcp_f32_e32 v3, v2
	v_mfma_f32_16x16x32_f16 v[64:67], v[100:103], v[124:127], v[64:67]
	v_med3_f32 v16, v16, s57, v194
	global_store_short v[52:53], v1, off
	v_fma_f32 v1, -v2, v3, 1.0
	v_fmac_f32_e32 v3, v1, v3
	v_div_scale_f32 v1, vcc, v62, v0, v62
	v_mul_f32_e32 v60, v1, v3
	v_fma_f32 v8, -v2, v60, v1
	v_fmac_f32_e32 v60, v8, v3
	v_fma_f32 v1, -v2, v60, v1
	v_div_fmas_f32 v1, v1, v3, v60
	v_mfma_f32_16x16x32_f16 v[8:11], v[132:135], v[116:119], v[12:15]
	v_cvt_f16_f32_e32 v16, v16
	global_store_short v[148:149], v16, off
	s_nop 0
	v_div_fixup_f32 v12, v1, v0, v62
	v_mul_f32_e32 v54, v54, v12
	v_mul_f32_e32 v12, 0xbfb8aa3b, v63
	v_exp_f32_e32 v60, v12
	v_mfma_f32_16x16x32_f16 v[0:3], v[132:135], v[108:111], v[68:71]
	v_add_f32_e32 v62, 1.0, v60
	v_mfma_f32_16x16x32_f16 v[12:15], v[132:135], v[128:131], v[4:7]
	s_nop 0
	v_div_scale_f32 v68, s[2:3], v62, v62, v63
	v_rcp_f32_e32 v69, v68
	v_med3_f32 v4, v54, s57, v194
	v_cvt_f16_f32_e32 v54, v4
	v_mad_i64_i32 v[60:61], s[2:3], v51, s64, v[48:49]
	v_or_b32_e32 v51, 3, v50
	global_store_short v[60:61], v54, off
	v_fma_f32 v54, -v68, v69, 1.0
	v_fmac_f32_e32 v69, v54, v69
	v_div_scale_f32 v54, vcc, v63, v62, v63
	v_mul_f32_e32 v70, v54, v69
	v_fma_f32 v71, -v68, v70, v54
	v_fmac_f32_e32 v70, v71, v69
	v_fma_f32 v54, -v68, v70, v54
	v_mul_f32_e32 v68, 0xbfb8aa3b, v56
	v_exp_f32_e32 v68, v68
	v_div_fmas_f32 v54, v54, v69, v70
	v_div_fixup_f32 v54, v54, v62, v63
	v_mul_f32_e32 v54, v55, v54
	v_add_f32_e32 v62, 1.0, v68
	v_div_scale_f32 v63, s[2:3], v62, v62, v56
	v_rcp_f32_e32 v68, v63
	v_med3_f32 v54, v54, s57, v194
	v_cvt_f16_f32_e32 v69, v54
	v_mad_i64_i32 v[54:55], s[2:3], v51, s64, v[48:49]
	v_fma_f32 v51, -v63, v68, 1.0
	v_fmac_f32_e32 v68, v51, v68
	v_div_scale_f32 v51, vcc, v56, v62, v56
	v_mul_f32_e32 v70, v51, v68
	v_fma_f32 v71, -v63, v70, v51
	v_fmac_f32_e32 v70, v71, v68
	v_fma_f32 v51, -v63, v70, v51
	v_mul_f32_e32 v63, 0xbfb8aa3b, v57
	v_exp_f32_e32 v63, v63
	v_div_fmas_f32 v51, v51, v68, v70
	v_div_fixup_f32 v51, v51, v62, v56
	v_mul_f32_e32 v51, v64, v51
	v_add_f32_e32 v56, 1.0, v63
	v_div_scale_f32 v62, s[2:3], v56, v56, v57
	v_rcp_f32_e32 v63, v62
	v_med3_f32 v51, v51, s57, v194
	v_cvt_f16_f32_e32 v51, v51
	v_mfma_f32_16x16x32_f16 v[40:43], v[104:107], v[116:119], v[44:47]
	v_fma_f32 v64, -v62, v63, 1.0
	v_fmac_f32_e32 v63, v64, v63
	v_div_scale_f32 v64, vcc, v57, v56, v57
	v_mul_f32_e32 v68, v64, v63
	v_fma_f32 v70, -v62, v68, v64
	v_fmac_f32_e32 v68, v70, v63
	v_fma_f32 v62, -v62, v68, v64
	v_div_fmas_f32 v62, v62, v63, v68
	v_div_fixup_f32 v56, v62, v56, v57
	v_mul_f32_e32 v57, 0xbfb8aa3b, v58
	v_exp_f32_e32 v57, v57
	v_mul_f32_e32 v56, v65, v56
	v_med3_f32 v56, v56, s57, v194
	v_cvt_f16_f32_e32 v56, v56
	v_add_f32_e32 v57, 1.0, v57
	v_div_scale_f32 v62, s[2:3], v57, v57, v58
	v_rcp_f32_e32 v63, v62
	global_store_short v[54:55], v69, off
	global_store_short v[148:149], v51, off offset:32
	global_store_short v[52:53], v56, off offset:32
	v_mfma_f32_16x16x32_f16 v[44:47], v[104:107], v[128:131], v[36:39]
	v_fma_f32 v51, -v62, v63, 1.0
	v_fmac_f32_e32 v63, v51, v63
	v_div_scale_f32 v51, vcc, v58, v57, v58
	v_mul_f32_e32 v52, v51, v63
	v_fma_f32 v53, -v62, v52, v51
	v_fmac_f32_e32 v52, v53, v63
	v_mul_f32_e32 v53, 0xbfb8aa3b, v59
	v_exp_f32_e32 v53, v53
	v_fma_f32 v51, -v62, v52, v51
	v_div_fmas_f32 v51, v51, v63, v52
	v_div_fixup_f32 v51, v51, v57, v58
	v_add_f32_e32 v52, 1.0, v53
	v_div_scale_f32 v53, s[2:3], v52, v52, v59
	v_rcp_f32_e32 v56, v53
	v_mul_f32_e32 v51, v66, v51
	v_med3_f32 v51, v51, s57, v194
	v_cvt_f16_f32_e32 v51, v51
	v_fma_f32 v57, -v53, v56, 1.0
	v_fmac_f32_e32 v56, v57, v56
	v_div_scale_f32 v57, vcc, v59, v52, v59
	v_mul_f32_e32 v58, v57, v56
	v_fma_f32 v62, -v53, v58, v57
	v_fmac_f32_e32 v58, v62, v56
	v_fma_f32 v53, -v53, v58, v57
	v_div_fmas_f32 v53, v53, v56, v58
	v_div_fixup_f32 v52, v53, v52, v59
	v_mul_f32_e32 v53, 0xbfb8aa3b, v40
	v_exp_f32_e32 v53, v53
	v_mul_f32_e32 v52, v67, v52
	v_med3_f32 v52, v52, s57, v194
	v_cvt_f16_f32_e32 v52, v52
	v_add_f32_e32 v53, 1.0, v53
	v_div_scale_f32 v56, s[2:3], v53, v53, v40
	v_rcp_f32_e32 v57, v56
	global_store_short v[60:61], v51, off offset:32
	global_store_short v[54:55], v52, off offset:32
	v_or_b32_e32 v51, 16, v50
	v_mfma_f32_16x16x32_f16 v[32:35], v[104:107], v[108:111], v[120:123]
	v_fma_f32 v52, -v56, v57, 1.0
	v_fmac_f32_e32 v57, v52, v57
	v_div_scale_f32 v52, vcc, v40, v53, v40
	v_mul_f32_e32 v54, v52, v57
	v_fma_f32 v55, -v56, v54, v52
	v_fmac_f32_e32 v54, v55, v57
	v_fma_f32 v52, -v56, v54, v52
	v_div_fmas_f32 v52, v52, v57, v54
	v_div_fixup_f32 v40, v52, v53, v40
	v_mul_f32_e32 v52, 0xbfb8aa3b, v41
	v_exp_f32_e32 v52, v52
	v_mul_f32_e32 v40, v44, v40
	v_mfma_f32_16x16x32_f16 v[36:39], v[104:107], v[124:127], v[96:99]
	v_med3_f32 v40, v40, s57, v194
	v_add_f32_e32 v44, 1.0, v52
	v_div_scale_f32 v54, s[2:3], v44, v44, v41
	v_rcp_f32_e32 v55, v54
	v_mad_i64_i32 v[52:53], s[2:3], v51, s64, v[48:49]
	v_cvt_f16_f32_e32 v40, v40
	v_fma_f32 v51, -v54, v55, 1.0
	v_fmac_f32_e32 v55, v51, v55
	v_div_scale_f32 v51, vcc, v41, v44, v41
	v_mul_f32_e32 v56, v51, v55
	v_fma_f32 v57, -v54, v56, v51
	v_fmac_f32_e32 v56, v57, v55
	v_fma_f32 v51, -v54, v56, v51
	v_div_fmas_f32 v51, v51, v55, v56
	v_div_fixup_f32 v41, v51, v44, v41
	v_mul_f32_e32 v44, 0xbfb8aa3b, v42
	v_exp_f32_e32 v44, v44
	v_mul_f32_e32 v41, v45, v41
	v_med3_f32 v41, v41, s57, v194
	v_cvt_f16_f32_e32 v45, v41
	v_add_f32_e32 v44, 1.0, v44
	v_div_scale_f32 v51, s[2:3], v44, v44, v42
	v_rcp_f32_e32 v54, v51
	global_store_short v[52:53], v40, off
	v_or_b32_e32 v40, 17, v50
	v_mad_i64_i32 v[40:41], s[2:3], v40, s64, v[48:49]
	v_fma_f32 v55, -v51, v54, 1.0
	v_fmac_f32_e32 v54, v55, v54
	v_div_scale_f32 v55, vcc, v42, v44, v42
	v_mul_f32_e32 v56, v55, v54
	v_fma_f32 v57, -v51, v56, v55
	v_fmac_f32_e32 v56, v57, v54
	v_fma_f32 v51, -v51, v56, v55
	v_div_fmas_f32 v51, v51, v54, v56
	v_div_fixup_f32 v42, v51, v44, v42
	v_mul_f32_e32 v44, 0xbfb8aa3b, v43
	v_exp_f32_e32 v44, v44
	v_mul_f32_e32 v42, v46, v42
	v_med3_f32 v42, v42, s57, v194
	v_cvt_f16_f32_e32 v42, v42
	v_add_f32_e32 v46, 1.0, v44
	v_div_scale_f32 v51, s[2:3], v46, v46, v43
	v_rcp_f32_e32 v54, v51
	global_store_short v[40:41], v45, off
	v_or_b32_e32 v45, 18, v50
	v_mad_i64_i32 v[44:45], s[2:3], v45, s64, v[48:49]
	v_fma_f32 v55, -v51, v54, 1.0
	v_fmac_f32_e32 v54, v55, v54
	v_div_scale_f32 v55, vcc, v43, v46, v43
	v_mul_f32_e32 v56, v55, v54
	v_fma_f32 v57, -v51, v56, v55
	v_fmac_f32_e32 v56, v57, v54
	v_fma_f32 v51, -v51, v56, v55
	v_div_fmas_f32 v51, v51, v54, v56
	v_mul_f32_e32 v54, 0xbfb8aa3b, v32
	v_exp_f32_e32 v54, v54
	v_div_fixup_f32 v43, v51, v46, v43
	v_mul_f32_e32 v43, v47, v43
	v_med3_f32 v43, v43, s57, v194
	v_add_f32_e32 v46, 1.0, v54
	v_div_scale_f32 v47, s[2:3], v46, v46, v32
	v_rcp_f32_e32 v51, v47
	v_cvt_f16_f32_e32 v54, v43
	global_store_short v[44:45], v42, off
	v_or_b32_e32 v42, 19, v50
	v_fma_f32 v55, -v47, v51, 1.0
	v_fmac_f32_e32 v51, v55, v51
	v_div_scale_f32 v55, vcc, v32, v46, v32
	v_mul_f32_e32 v56, v55, v51
	v_fma_f32 v57, -v47, v56, v55
	v_fmac_f32_e32 v56, v57, v51
	v_fma_f32 v47, -v47, v56, v55
	v_mul_f32_e32 v55, 0xbfb8aa3b, v33
	v_exp_f32_e32 v55, v55
	v_div_fmas_f32 v47, v47, v51, v56
	v_div_fixup_f32 v32, v47, v46, v32
	v_mul_f32_e32 v32, v36, v32
	v_add_f32_e32 v46, 1.0, v55
	v_div_scale_f32 v47, s[2:3], v46, v46, v33
	v_rcp_f32_e32 v51, v47
	v_med3_f32 v32, v32, s57, v194
	v_cvt_f16_f32_e32 v32, v32
	v_mad_i64_i32 v[42:43], s[2:3], v42, s64, v[48:49]
	v_fma_f32 v36, -v47, v51, 1.0
	v_fmac_f32_e32 v51, v36, v51
	v_div_scale_f32 v36, vcc, v33, v46, v33
	v_mul_f32_e32 v55, v36, v51
	v_fma_f32 v56, -v47, v55, v36
	v_fmac_f32_e32 v55, v56, v51
	v_fma_f32 v36, -v47, v55, v36
	v_div_fmas_f32 v36, v36, v51, v55
	v_div_fixup_f32 v33, v36, v46, v33
	v_mul_f32_e32 v36, 0xbfb8aa3b, v34
	v_exp_f32_e32 v36, v36
	v_mul_f32_e32 v33, v37, v33
	v_med3_f32 v33, v33, s57, v194
	v_cvt_f16_f32_e32 v33, v33
	v_add_f32_e32 v36, 1.0, v36
	v_div_scale_f32 v37, s[2:3], v36, v36, v34
	v_rcp_f32_e32 v46, v37
	global_store_short v[42:43], v54, off
	global_store_short v[52:53], v32, off offset:32
	global_store_short v[40:41], v33, off offset:32
	v_mfma_f32_16x16x32_f16 v[24:27], v[136:139], v[116:119], v[28:31]
	v_fma_f32 v32, -v37, v46, 1.0
	v_fmac_f32_e32 v46, v32, v46
	v_div_scale_f32 v32, vcc, v34, v36, v34
	v_mul_f32_e32 v33, v32, v46
	v_fma_f32 v40, -v37, v33, v32
	v_fmac_f32_e32 v33, v40, v46
	v_fma_f32 v32, -v37, v33, v32
	v_mul_f32_e32 v37, 0xbfb8aa3b, v35
	v_exp_f32_e32 v37, v37
	v_div_fmas_f32 v32, v32, v46, v33
	v_div_fixup_f32 v32, v32, v36, v34
	v_mul_f32_e32 v32, v38, v32
	v_add_f32_e32 v33, 1.0, v37
	v_div_scale_f32 v34, s[2:3], v33, v33, v35
	v_rcp_f32_e32 v36, v34
	v_med3_f32 v32, v32, s57, v194
	v_cvt_f16_f32_e32 v32, v32
	v_mfma_f32_16x16x32_f16 v[28:31], v[136:139], v[128:131], v[20:23]
	v_fma_f32 v37, -v34, v36, 1.0
	v_fmac_f32_e32 v36, v37, v36
	v_div_scale_f32 v37, vcc, v35, v33, v35
	v_mul_f32_e32 v38, v37, v36
	v_fma_f32 v40, -v34, v38, v37
	v_fmac_f32_e32 v38, v40, v36
	v_fma_f32 v34, -v34, v38, v37
	v_div_fmas_f32 v34, v34, v36, v38
	v_div_fixup_f32 v33, v34, v33, v35
	v_mul_f32_e32 v34, 0xbfb8aa3b, v24
	v_exp_f32_e32 v34, v34
	v_mul_f32_e32 v33, v39, v33
	v_med3_f32 v33, v33, s57, v194
	v_cvt_f16_f32_e32 v33, v33
	v_add_f32_e32 v34, 1.0, v34
	v_div_scale_f32 v35, s[2:3], v34, v34, v24
	v_rcp_f32_e32 v36, v35
	global_store_short v[44:45], v32, off offset:32
	global_store_short v[42:43], v33, off offset:32
	v_mfma_f32_16x16x32_f16 v[16:19], v[136:139], v[108:111], v[144:147]
	v_or_b32_e32 v32, 32, v50
	v_fma_f32 v33, -v35, v36, 1.0
	v_fmac_f32_e32 v36, v33, v36
	v_div_scale_f32 v33, vcc, v24, v34, v24
	v_mul_f32_e32 v37, v33, v36
	v_fma_f32 v38, -v35, v37, v33
	v_fmac_f32_e32 v37, v38, v36
	v_fma_f32 v33, -v35, v37, v33
	v_div_fmas_f32 v33, v33, v36, v37
	v_div_fixup_f32 v24, v33, v34, v24
	v_mul_f32_e32 v33, 0xbfb8aa3b, v25
	v_exp_f32_e32 v33, v33
	v_mul_f32_e32 v24, v28, v24
	v_mfma_f32_16x16x32_f16 v[20:23], v[136:139], v[124:127], v[140:143]
	v_med3_f32 v24, v24, s57, v194
	v_add_f32_e32 v28, 1.0, v33
	v_div_scale_f32 v34, s[2:3], v28, v28, v25
	v_rcp_f32_e32 v35, v34
	v_cvt_f16_f32_e32 v24, v24
	v_mad_i64_i32 v[32:33], s[2:3], v32, s64, v[48:49]
	v_fma_f32 v36, -v34, v35, 1.0
	v_fmac_f32_e32 v35, v36, v35
	v_div_scale_f32 v36, vcc, v25, v28, v25
	v_mul_f32_e32 v37, v36, v35
	v_fma_f32 v38, -v34, v37, v36
	v_fmac_f32_e32 v37, v38, v35
	v_fma_f32 v34, -v34, v37, v36
	v_div_fmas_f32 v34, v34, v35, v37
	v_div_fixup_f32 v25, v34, v28, v25
	v_mul_f32_e32 v28, 0xbfb8aa3b, v26
	v_exp_f32_e32 v28, v28
	v_mul_f32_e32 v25, v29, v25
	v_med3_f32 v25, v25, s57, v194
	v_cvt_f16_f32_e32 v29, v25
	v_add_f32_e32 v28, 1.0, v28
	v_div_scale_f32 v34, s[2:3], v28, v28, v26
	v_rcp_f32_e32 v35, v34
	global_store_short v[32:33], v24, off
	v_or_b32_e32 v24, 33, v50
	v_mad_i64_i32 v[24:25], s[2:3], v24, s64, v[48:49]
	v_fma_f32 v36, -v34, v35, 1.0
	v_fmac_f32_e32 v35, v36, v35
	v_div_scale_f32 v36, vcc, v26, v28, v26
	v_mul_f32_e32 v37, v36, v35
	v_fma_f32 v38, -v34, v37, v36
	v_fmac_f32_e32 v37, v38, v35
	v_fma_f32 v34, -v34, v37, v36
	v_div_fmas_f32 v34, v34, v35, v37
	v_div_fixup_f32 v26, v34, v28, v26
	v_mul_f32_e32 v28, 0xbfb8aa3b, v27
	v_exp_f32_e32 v28, v28
	v_mul_f32_e32 v26, v30, v26
	v_med3_f32 v26, v26, s57, v194
	v_cvt_f16_f32_e32 v26, v26
	v_add_f32_e32 v30, 1.0, v28
	v_div_scale_f32 v34, s[2:3], v30, v30, v27
	v_rcp_f32_e32 v35, v34
	global_store_short v[24:25], v29, off
	v_or_b32_e32 v29, 34, v50
	v_mad_i64_i32 v[28:29], s[2:3], v29, s64, v[48:49]
	v_fma_f32 v36, -v34, v35, 1.0
	v_fmac_f32_e32 v35, v36, v35
	v_div_scale_f32 v36, vcc, v27, v30, v27
	v_mul_f32_e32 v37, v36, v35
	v_fma_f32 v38, -v34, v37, v36
	v_fmac_f32_e32 v37, v38, v35
	v_fma_f32 v34, -v34, v37, v36
	v_div_fmas_f32 v34, v34, v35, v37
	v_mul_f32_e32 v35, 0xbfb8aa3b, v16
	v_exp_f32_e32 v35, v35
	v_div_fixup_f32 v27, v34, v30, v27
	v_mul_f32_e32 v27, v31, v27
	v_med3_f32 v27, v27, s57, v194
	v_add_f32_e32 v30, 1.0, v35
	v_div_scale_f32 v31, s[2:3], v30, v30, v16
	v_rcp_f32_e32 v34, v31
	v_cvt_f16_f32_e32 v35, v27
	global_store_short v[28:29], v26, off
	v_or_b32_e32 v26, 35, v50
	v_fma_f32 v36, -v31, v34, 1.0
	v_fmac_f32_e32 v34, v36, v34
	v_div_scale_f32 v36, vcc, v16, v30, v16
	v_mul_f32_e32 v37, v36, v34
	v_fma_f32 v38, -v31, v37, v36
	v_fmac_f32_e32 v37, v38, v34
	v_fma_f32 v31, -v31, v37, v36
	v_mul_f32_e32 v36, 0xbfb8aa3b, v17
	v_exp_f32_e32 v36, v36
	v_div_fmas_f32 v31, v31, v34, v37
	v_div_fixup_f32 v16, v31, v30, v16
	v_mul_f32_e32 v16, v20, v16
	v_add_f32_e32 v30, 1.0, v36
	v_div_scale_f32 v31, s[2:3], v30, v30, v17
	v_rcp_f32_e32 v34, v31
	v_med3_f32 v16, v16, s57, v194
	v_cvt_f16_f32_e32 v16, v16
	v_mad_i64_i32 v[26:27], s[2:3], v26, s64, v[48:49]
	v_fma_f32 v20, -v31, v34, 1.0
	v_fmac_f32_e32 v34, v20, v34
	v_div_scale_f32 v20, vcc, v17, v30, v17
	v_mul_f32_e32 v36, v20, v34
	v_fma_f32 v37, -v31, v36, v20
	v_fmac_f32_e32 v36, v37, v34
	v_fma_f32 v20, -v31, v36, v20
	v_div_fmas_f32 v20, v20, v34, v36
	v_div_fixup_f32 v17, v20, v30, v17
	v_mul_f32_e32 v20, 0xbfb8aa3b, v18
	v_exp_f32_e32 v20, v20
	v_mul_f32_e32 v17, v21, v17
	v_med3_f32 v17, v17, s57, v194
	v_cvt_f16_f32_e32 v17, v17
	v_add_f32_e32 v20, 1.0, v20
	v_div_scale_f32 v21, s[2:3], v20, v20, v18
	v_rcp_f32_e32 v30, v21
	global_store_short v[26:27], v35, off
	global_store_short v[32:33], v16, off offset:32
	global_store_short v[24:25], v17, off offset:32
	v_mfma_f32_16x16x32_f16 v[4:7], v[132:135], v[124:127], v[72:75]
	v_fma_f32 v16, -v21, v30, 1.0
	v_fmac_f32_e32 v30, v16, v30
	v_div_scale_f32 v16, vcc, v18, v20, v18
	v_mul_f32_e32 v17, v16, v30
	v_fma_f32 v24, -v21, v17, v16
	v_fmac_f32_e32 v17, v24, v30
	v_fma_f32 v16, -v21, v17, v16
	v_mul_f32_e32 v21, 0xbfb8aa3b, v19
	v_exp_f32_e32 v21, v21
	v_div_fmas_f32 v16, v16, v30, v17
	v_div_fixup_f32 v16, v16, v20, v18
	v_mul_f32_e32 v16, v22, v16
	v_add_f32_e32 v17, 1.0, v21
	v_div_scale_f32 v18, s[2:3], v17, v17, v19
	v_rcp_f32_e32 v20, v18
	v_med3_f32 v16, v16, s57, v194
	v_cvt_f16_f32_e32 v16, v16
	v_fma_f32 v21, -v18, v20, 1.0
	v_fmac_f32_e32 v20, v21, v20
	v_div_scale_f32 v21, vcc, v19, v17, v19
	v_mul_f32_e32 v22, v21, v20
	v_fma_f32 v24, -v18, v22, v21
	v_fmac_f32_e32 v22, v24, v20
	v_fma_f32 v18, -v18, v22, v21
	v_div_fmas_f32 v18, v18, v20, v22
	v_div_fixup_f32 v17, v18, v17, v19
	v_mul_f32_e32 v18, 0xbfb8aa3b, v8
	v_exp_f32_e32 v18, v18
	v_mul_f32_e32 v17, v23, v17
	v_med3_f32 v17, v17, s57, v194
	v_cvt_f16_f32_e32 v17, v17
	v_add_f32_e32 v18, 1.0, v18
	v_div_scale_f32 v19, s[2:3], v18, v18, v8
	v_rcp_f32_e32 v20, v19
	global_store_short v[28:29], v16, off offset:32
	global_store_short v[26:27], v17, off offset:32
	v_or_b32_e32 v16, 48, v50
	v_fma_f32 v17, -v19, v20, 1.0
	v_fmac_f32_e32 v20, v17, v20
	v_div_scale_f32 v17, vcc, v8, v18, v8
	v_mul_f32_e32 v21, v17, v20
	v_fma_f32 v22, -v19, v21, v17
	v_fmac_f32_e32 v21, v22, v20
	v_fma_f32 v17, -v19, v21, v17
	v_div_fmas_f32 v17, v17, v20, v21
	v_div_fixup_f32 v8, v17, v18, v8
	v_mul_f32_e32 v17, 0xbfb8aa3b, v9
	v_exp_f32_e32 v17, v17
	v_mul_f32_e32 v8, v12, v8
	v_med3_f32 v8, v8, s57, v194
	v_cvt_f16_f32_e32 v8, v8
	v_add_f32_e32 v12, 1.0, v17
	v_div_scale_f32 v18, s[2:3], v12, v12, v9
	v_rcp_f32_e32 v19, v18
	v_mad_i64_i32 v[16:17], s[2:3], v16, s64, v[48:49]
	global_store_short v[16:17], v8, off
	v_fma_f32 v20, -v18, v19, 1.0
	v_fmac_f32_e32 v19, v20, v19
	v_div_scale_f32 v20, vcc, v9, v12, v9
	v_mul_f32_e32 v21, v20, v19
	v_fma_f32 v22, -v18, v21, v20
	v_fmac_f32_e32 v21, v22, v19
	v_fma_f32 v18, -v18, v21, v20
	v_div_fmas_f32 v18, v18, v19, v21
	v_div_fixup_f32 v9, v18, v12, v9
	v_mul_f32_e32 v12, 0xbfb8aa3b, v10
	v_exp_f32_e32 v12, v12
	v_mul_f32_e32 v9, v13, v9
	v_med3_f32 v9, v9, s57, v194
	v_cvt_f16_f32_e32 v13, v9
	v_add_f32_e32 v12, 1.0, v12
	v_div_scale_f32 v18, s[2:3], v12, v12, v10
	v_rcp_f32_e32 v19, v18
	v_or_b32_e32 v8, 49, v50
	v_mad_i64_i32 v[8:9], s[2:3], v8, s64, v[48:49]
	v_fma_f32 v20, -v18, v19, 1.0
	v_fmac_f32_e32 v19, v20, v19
	v_div_scale_f32 v20, vcc, v10, v12, v10
	v_mul_f32_e32 v21, v20, v19
	v_fma_f32 v22, -v18, v21, v20
	v_fmac_f32_e32 v21, v22, v19
	v_fma_f32 v18, -v18, v21, v20
	v_div_fmas_f32 v18, v18, v19, v21
	v_div_fixup_f32 v10, v18, v12, v10
	v_mul_f32_e32 v12, 0xbfb8aa3b, v11
	v_exp_f32_e32 v12, v12
	v_mul_f32_e32 v10, v14, v10
	v_med3_f32 v10, v10, s57, v194
	v_cvt_f16_f32_e32 v10, v10
	v_add_f32_e32 v14, 1.0, v12
	v_div_scale_f32 v18, s[2:3], v14, v14, v11
	v_rcp_f32_e32 v19, v18
	global_store_short v[8:9], v13, off
	v_or_b32_e32 v13, 50, v50
	v_mad_i64_i32 v[12:13], s[2:3], v13, s64, v[48:49]
	v_fma_f32 v20, -v18, v19, 1.0
	v_fmac_f32_e32 v19, v20, v19
	v_div_scale_f32 v20, vcc, v11, v14, v11
	v_mul_f32_e32 v21, v20, v19
	v_fma_f32 v22, -v18, v21, v20
	v_fmac_f32_e32 v21, v22, v19
	v_fma_f32 v18, -v18, v21, v20
	v_div_fmas_f32 v18, v18, v19, v21
	v_mul_f32_e32 v19, 0xbfb8aa3b, v0
	v_exp_f32_e32 v19, v19
	v_div_fixup_f32 v11, v18, v14, v11
	v_mul_f32_e32 v11, v15, v11
	v_med3_f32 v11, v11, s57, v194
	v_add_f32_e32 v14, 1.0, v19
	v_div_scale_f32 v15, s[2:3], v14, v14, v0
	v_rcp_f32_e32 v18, v15
	v_cvt_f16_f32_e32 v19, v11
	global_store_short v[12:13], v10, off
	v_or_b32_e32 v10, 51, v50
	v_fma_f32 v20, -v15, v18, 1.0
	v_fmac_f32_e32 v18, v20, v18
	v_div_scale_f32 v20, vcc, v0, v14, v0
	v_mul_f32_e32 v21, v20, v18
	v_fma_f32 v22, -v15, v21, v20
	v_fmac_f32_e32 v21, v22, v18
	v_fma_f32 v15, -v15, v21, v20
	v_mul_f32_e32 v20, 0xbfb8aa3b, v1
	v_exp_f32_e32 v20, v20
	v_div_fmas_f32 v15, v15, v18, v21
	v_div_fixup_f32 v0, v15, v14, v0
	v_mul_f32_e32 v0, v4, v0
	v_add_f32_e32 v14, 1.0, v20
	v_div_scale_f32 v15, s[2:3], v14, v14, v1
	v_rcp_f32_e32 v18, v15
	v_med3_f32 v0, v0, s57, v194
	v_cvt_f16_f32_e32 v0, v0
	v_mad_i64_i32 v[10:11], s[2:3], v10, s64, v[48:49]
	v_fma_f32 v4, -v15, v18, 1.0
	v_fmac_f32_e32 v18, v4, v18
	v_div_scale_f32 v4, vcc, v1, v14, v1
	v_mul_f32_e32 v20, v4, v18
	v_fma_f32 v21, -v15, v20, v4
	v_fmac_f32_e32 v20, v21, v18
	v_fma_f32 v4, -v15, v20, v4
	v_div_fmas_f32 v4, v4, v18, v20
	v_div_fixup_f32 v1, v4, v14, v1
	v_mul_f32_e32 v4, 0xbfb8aa3b, v2
	v_exp_f32_e32 v4, v4
	v_mul_f32_e32 v1, v5, v1
	v_med3_f32 v1, v1, s57, v194
	v_cvt_f16_f32_e32 v1, v1
	v_add_f32_e32 v4, 1.0, v4
	v_div_scale_f32 v5, s[2:3], v4, v4, v2
	v_rcp_f32_e32 v14, v5
	global_store_short v[10:11], v19, off
	global_store_short v[16:17], v0, off offset:32
	global_store_short v[8:9], v1, off offset:32
	v_fma_f32 v0, -v5, v14, 1.0
	v_fmac_f32_e32 v14, v0, v14
	v_div_scale_f32 v0, vcc, v2, v4, v2
	v_mul_f32_e32 v1, v0, v14
	v_fma_f32 v8, -v5, v1, v0
	v_fmac_f32_e32 v1, v8, v14
	v_fma_f32 v0, -v5, v1, v0
	v_mul_f32_e32 v5, 0xbfb8aa3b, v3
	v_exp_f32_e32 v5, v5
	v_div_fmas_f32 v0, v0, v14, v1
	v_div_fixup_f32 v0, v0, v4, v2
	v_mul_f32_e32 v0, v6, v0
	v_add_f32_e32 v1, 1.0, v5
	v_div_scale_f32 v2, s[2:3], v1, v1, v3
	v_rcp_f32_e32 v4, v2
	v_med3_f32 v0, v0, s57, v194
	v_cvt_f16_f32_e32 v0, v0
	v_fma_f32 v5, -v2, v4, 1.0
	v_fmac_f32_e32 v4, v5, v4
	v_div_scale_f32 v5, vcc, v3, v1, v3
	v_mul_f32_e32 v6, v5, v4
	v_fma_f32 v8, -v2, v6, v5
	v_fmac_f32_e32 v6, v8, v4
	v_fma_f32 v2, -v2, v6, v5
	v_div_fmas_f32 v2, v2, v4, v6
	v_div_fixup_f32 v1, v2, v1, v3
	v_mul_f32_e32 v1, v7, v1
	v_med3_f32 v1, v1, s57, v194
	v_cvt_f16_f32_e32 v1, v1
	global_store_short v[12:13], v0, off offset:32
	global_store_short v[10:11], v1, off offset:32
	s_cbranch_scc0 .LBB0_631

	.amdhsa_kernel _Z14fwd_megakernel6Params
		.amdhsa_group_segment_fixed_size 73732
		.amdhsa_private_segment_fixed_size 0
		.amdhsa_kernarg_size 432
		.amdhsa_user_sgpr_count 2
		.amdhsa_user_sgpr_dispatch_ptr 0
		.amdhsa_user_sgpr_queue_ptr 0
		.amdhsa_user_sgpr_kernarg_segment_ptr 1
		.amdhsa_user_sgpr_dispatch_id 0
		.amdhsa_user_sgpr_kernarg_preload_length 0
		.amdhsa_user_sgpr_kernarg_preload_offset 0
		.amdhsa_user_sgpr_private_segment_size 0
		.amdhsa_uses_dynamic_stack 0
		.amdhsa_enable_private_segment 0
		.amdhsa_system_sgpr_workgroup_id_x 1
		.amdhsa_system_sgpr_workgroup_id_y 0
		.amdhsa_system_sgpr_workgroup_id_z 0
		.amdhsa_system_sgpr_workgroup_info 0
		.amdhsa_system_vgpr_workitem_id 2
		.amdhsa_next_free_vgpr 252
		.amdhsa_next_free_sgpr 102
		.amdhsa_accum_offset 252
		.amdhsa_reserve_vcc 1
		.amdhsa_float_round_mode_32 0
		.amdhsa_float_round_mode_16_64 0
		.amdhsa_float_denorm_mode_32 3
		.amdhsa_float_denorm_mode_16_64 3
		.amdhsa_dx10_clamp 1
		.amdhsa_ieee_mode 1
		.amdhsa_fp16_overflow 0
		.amdhsa_tg_split 0
		.amdhsa_exception_fp_ieee_invalid_op 0
		.amdhsa_exception_fp_denorm_src 0
		.amdhsa_exception_fp_ieee_div_zero 0
		.amdhsa_exception_fp_ieee_overflow 0
		.amdhsa_exception_fp_ieee_underflow 0
		.amdhsa_exception_fp_ieee_inexact 0
		.amdhsa_exception_int_div_zero 0
	.end_amdhsa_kernel

amdhsa.kernels:
  - .agpr_count:     0
    .args:
      - .offset:         0
        .size:           176
        .value_kind:     by_value
      - .offset:         176
        .size:           4
        .value_kind:     hidden_block_count_x
      - .offset:         180
        .size:           4
        .value_kind:     hidden_block_count_y
      - .offset:         184
        .size:           4
        .value_kind:     hidden_block_count_z
      - .offset:         188
        .size:           2
        .value_kind:     hidden_group_size_x
      - .offset:         190
        .size:           2
        .value_kind:     hidden_group_size_y
      - .offset:         192
        .size:           2
        .value_kind:     hidden_group_size_z
      - .offset:         194
        .size:           2
        .value_kind:     hidden_remainder_x
      - .offset:         196
        .size:           2
        .value_kind:     hidden_remainder_y
      - .offset:         198
        .size:           2
        .value_kind:     hidden_remainder_z
      - .offset:         216
        .size:           8
        .value_kind:     hidden_global_offset_x
      - .offset:         224
        .size:           8
        .value_kind:     hidden_global_offset_y
      - .offset:         232
        .size:           8
        .value_kind:     hidden_global_offset_z
      - .offset:         240
        .size:           2
        .value_kind:     hidden_grid_dims
      - .offset:         264
        .size:           8
        .value_kind:     hidden_multigrid_sync_arg
    .group_segment_fixed_size: 73732
    .kernarg_segment_align: 8
    .kernarg_segment_size: 432
    .language:       OpenCL C
    .language_version:
      - 2
      - 0
    .max_flat_workgroup_size: 256
    .name:           _Z14fwd_megakernel6Params
    .private_segment_fixed_size: 0
    .sgpr_count:     108
    .sgpr_spill_count: 175
    .symbol:         _Z14fwd_megakernel6Params.kd
    .uniform_work_group_size: 1
    .uses_dynamic_stack: false
    .vgpr_count:     252
    .vgpr_spill_count: 0
    .wavefront_size: 64
